# M2 + mid-block s_setprio 0/1 pairs between the two 16-MFMA halves removed
# baseline (speedup 1.0000x reference)
; #define PG8_SB(B) __builtin_amdgcn_rcpf(1.f + expneg(B))
; #define PG8_SB(B) __builtin_amdgcn_rcpf(1.f + expneg(B))
; #define PG8_STAGE(bufoff, gbase, voff) do { _Pragma("unroll") for (int _i = 0; _i < 2; ++_i) \
;         __builtin_amdgcn_global_load_lds((const unsigned*)((const char*)(gbase) + (size_t)_i * qstep + (voff)[0]), (PG8_LAS unsigned*)(lds + (bufoff) + ldsw + _i * 8192), 16, 0, 0); } while (0)
; #define PG8_LDA(dst, b, h) do { _Pragma("unroll") for (int m = 0; m < 4; ++m) _Pragma("unroll") for (int k = 0; k < 2; ++k) dst[m][k] = *(const PG8_LAS bf16x8*)(lds + PG8_SA(b, h) + aoff + m * 2048 + k * 1024); } while (0)
; #define PG8_MMA(ai, bj, At, Bt) do { __builtin_amdgcn_s_setprio(1); _Pragma("unroll") for (int m = 0; m < 4; ++m) _Pragma("unroll") for (int n = 0; n < 2; ++n) _Pragma("unroll") for (int k = 0; k < 2; ++k) \
;         acc[ai][bj][m][n] = __builtin_amdgcn_mfma_f32_16x16x32_bf16(Bt[n][k], At[m][k], acc[ai][bj][m][n], 0, 0, 0); __builtin_amdgcn_s_setprio(0); } while (0)
; #define PG8_WAIT_V89() do { if constexpr (SLIVER) PG8_WAIT_V(9); else PG8_WAIT_V(8); } while (0)
; #define PG8_LDS_S(b) do { if constexpr (SLIVER) { Sf[0] = *(const PG8_LAS bf16x8*)(lds + STAGE_BYTES + (b) * 2048 + soff0); Sf[1] = *(const PG8_LAS bf16x8*)(lds + STAGE_BYTES + (b) * 2048 + (soff0 ^ 64)); } } while (0)
; #define PG8_WAIT_L(n) asm volatile("s_waitcnt lgkmcnt(" #n ")" ::: "memory")
; #define PG8_BAR __builtin_amdgcn_s_barrier()
; #define PG8_SCHED __builtin_amdgcn_sched_barrier(0)
; template <class Epi, class Sched, bool ALIGN_EPI = false, bool SP2 = false, bool SLIVER = false>
; __device__ __forceinline__ void gemm_phase(PG8_LAS unsigned char* lds, const Gemm g, const Sched& S, const Epi& E) {
;     ...
;             PG8_WAIT_V89(); PG8_WAIT_L(0); PG8_BAR; PG8_MMA(0, 0, At, B0); PG8_MMA(0, 1, At, B1); PG8_BAR; PG8_SCHED;
;             PG8_LDA(At, 0, 1); PG8_LDS_S(0); PG8_STAGE(PG8_SB(0, 0), b2, voffB); PG8_STAGE(PG8_SB(0, 1), b2 + hstep, voffB); PG8_STAGE(PG8_SA(0, 0), a2, voffA);
;             PG8_WAIT_V89(); PG8_WAIT_L(0); PG8_BAR; PG8_MMA(1, 0, At, B0); PG8_MMA(1, 1, At, B1); PG8_MMA_S(); PG8_BAR; PG8_SCHED;
.Lgin_skipw0:
	s_waitcnt lgkmcnt(0)
	s_setprio 1
	s_barrier
	v_mfma_f32_16x16x32_bf16 v[126:129], v[136:139], v[174:177], v[126:129]
	v_mfma_f32_16x16x32_bf16 v[122:125], v[150:153], v[174:177], v[122:125]
	v_mfma_f32_16x16x32_bf16 v[114:117], v[136:139], v[184:187], v[114:117]
	v_mfma_f32_16x16x32_bf16 v[106:109], v[150:153], v[184:187], v[106:109]
	v_mfma_f32_16x16x32_bf16 v[98:101], v[136:139], v[192:195], v[98:101]
	v_mfma_f32_16x16x32_bf16 v[90:93], v[150:153], v[192:195], v[90:93]
	v_mfma_f32_16x16x32_bf16 v[82:85], v[136:139], v[200:203], v[82:85]
	v_mfma_f32_16x16x32_bf16 v[74:77], v[150:153], v[200:203], v[74:77]
	v_mfma_f32_16x16x32_bf16 v[126:129], v[140:143], v[180:183], v[126:129]
	v_mfma_f32_16x16x32_bf16 v[122:125], v[154:157], v[180:183], v[122:125]
	v_mfma_f32_16x16x32_bf16 v[114:117], v[140:143], v[188:191], v[114:117]
	v_mfma_f32_16x16x32_bf16 v[106:109], v[154:157], v[188:191], v[106:109]
	v_mfma_f32_16x16x32_bf16 v[98:101], v[140:143], v[196:199], v[98:101]
	v_mfma_f32_16x16x32_bf16 v[90:93], v[154:157], v[196:199], v[90:93]
	v_mfma_f32_16x16x32_bf16 v[82:85], v[140:143], v[210:213], v[82:85]
	v_mfma_f32_16x16x32_bf16 v[74:77], v[154:157], v[210:213], v[74:77]
	v_mfma_f32_16x16x32_bf16 v[118:121], v[158:161], v[174:177], v[118:121]
	v_mfma_f32_16x16x32_bf16 v[110:113], v[166:169], v[174:177], v[110:113]
	v_mfma_f32_16x16x32_bf16 v[102:105], v[158:161], v[184:187], v[102:105]
	v_mfma_f32_16x16x32_bf16 v[94:97], v[166:169], v[184:187], v[94:97]
	v_mfma_f32_16x16x32_bf16 v[86:89], v[158:161], v[192:195], v[86:89]
	v_mfma_f32_16x16x32_bf16 v[78:81], v[166:169], v[192:195], v[78:81]
	v_mfma_f32_16x16x32_bf16 v[70:73], v[158:161], v[200:203], v[70:73]
	v_mfma_f32_16x16x32_bf16 v[66:69], v[166:169], v[200:203], v[66:69]
	v_mfma_f32_16x16x32_bf16 v[118:121], v[162:165], v[180:183], v[118:121]
	v_mfma_f32_16x16x32_bf16 v[110:113], v[170:173], v[180:183], v[110:113]
	v_mfma_f32_16x16x32_bf16 v[102:105], v[162:165], v[188:191], v[102:105]
	v_mfma_f32_16x16x32_bf16 v[94:97], v[170:173], v[188:191], v[94:97]
	v_mfma_f32_16x16x32_bf16 v[86:89], v[162:165], v[196:199], v[86:89]
	v_mfma_f32_16x16x32_bf16 v[78:81], v[170:173], v[196:199], v[78:81]
	v_mfma_f32_16x16x32_bf16 v[70:73], v[162:165], v[210:213], v[70:73]
	v_mfma_f32_16x16x32_bf16 v[66:69], v[170:173], v[210:213], v[66:69]
	s_barrier
	s_setprio 0
	s_add_i32 s77, s77, s53
	v_lshl_add_u64 v[146:147], s[78:79], 0, v[132:133]
	s_mov_b32 m0, s77
	ds_read_b128 v[174:177], v149 offset:16384
	ds_read_b128 v[180:183], v149 offset:17408
	ds_read_b128 v[184:187], v149 offset:18432
	ds_read_b128 v[188:191], v149 offset:19456
	ds_read_b128 v[192:195], v149 offset:20480
	ds_read_b128 v[196:199], v149 offset:21504
	ds_read_b128 v[200:203], v149 offset:22528
	ds_read_b128 v[210:213], v149 offset:23552
	global_load_lds_dwordx4 v[146:147], off
	v_lshl_add_u64 v[214:215], v[146:147], 0, s[20:21]
	s_add_i32 m0, s77, 0x2000
	s_add_i32 s77, s80, s53
	global_load_lds_dwordx4 v[214:215], off
	v_lshl_add_u64 v[214:215], v[146:147], 0, s[22:23]
	s_mov_b32 m0, s77
	s_nop 0
	global_load_lds_dwordx4 v[214:215], off
	v_lshl_add_u64 v[214:215], v[146:147], 0, s[24:25]
	s_add_i32 m0, s77, 0x2000
	s_nop 0
	global_load_lds_dwordx4 v[214:215], off
	v_lshl_add_u64 v[214:215], s[62:63], 0, v[130:131]
	s_mov_b32 m0, s91
	v_lshl_add_u64 v[216:217], v[214:215], 0, s[20:21]
	global_load_lds_dwordx4 v[214:215], off
	s_mov_b32 m0, s50
	s_nop 0
	global_load_lds_dwordx4 v[216:217], off
	s_cmp_eq_u32 s76, s101
	s_cbranch_scc1 .Lgin_skipw1
	s_waitcnt vmcnt(8)
.Lgin_skipw1:
	s_waitcnt lgkmcnt(0)
	s_setprio 1
	s_barrier
	v_mfma_f32_16x16x32_bf16 v[62:65], v[136:139], v[174:177], v[62:65]
	v_mfma_f32_16x16x32_bf16 v[58:61], v[150:153], v[174:177], v[58:61]
	v_mfma_f32_16x16x32_bf16 v[50:53], v[136:139], v[184:187], v[50:53]
	v_mfma_f32_16x16x32_bf16 v[42:45], v[150:153], v[184:187], v[42:45]
	v_mfma_f32_16x16x32_bf16 v[34:37], v[136:139], v[192:195], v[34:37]
	v_mfma_f32_16x16x32_bf16 v[26:29], v[150:153], v[192:195], v[26:29]
	v_mfma_f32_16x16x32_bf16 v[18:21], v[136:139], v[200:203], v[18:21]
	v_mfma_f32_16x16x32_bf16 v[10:13], v[150:153], v[200:203], v[10:13]
	v_mfma_f32_16x16x32_bf16 v[62:65], v[140:143], v[180:183], v[62:65]
	v_mfma_f32_16x16x32_bf16 v[58:61], v[154:157], v[180:183], v[58:61]
	v_mfma_f32_16x16x32_bf16 v[50:53], v[140:143], v[188:191], v[50:53]
	v_mfma_f32_16x16x32_bf16 v[42:45], v[154:157], v[188:191], v[42:45]
	v_mfma_f32_16x16x32_bf16 v[34:37], v[140:143], v[196:199], v[34:37]
	v_mfma_f32_16x16x32_bf16 v[26:29], v[154:157], v[196:199], v[26:29]
	v_mfma_f32_16x16x32_bf16 v[18:21], v[140:143], v[210:213], v[18:21]
	v_mfma_f32_16x16x32_bf16 v[10:13], v[154:157], v[210:213], v[10:13]
	v_mfma_f32_16x16x32_bf16 v[54:57], v[158:161], v[174:177], v[54:57]
	v_mfma_f32_16x16x32_bf16 v[46:49], v[166:169], v[174:177], v[46:49]
	v_mfma_f32_16x16x32_bf16 v[38:41], v[158:161], v[184:187], v[38:41]
	v_mfma_f32_16x16x32_bf16 v[30:33], v[166:169], v[184:187], v[30:33]
	v_mfma_f32_16x16x32_bf16 v[22:25], v[158:161], v[192:195], v[22:25]
	v_mfma_f32_16x16x32_bf16 v[14:17], v[166:169], v[192:195], v[14:17]
	v_mfma_f32_16x16x32_bf16 v[6:9], v[158:161], v[200:203], v[6:9]
	v_mfma_f32_16x16x32_bf16 v[2:5], v[166:169], v[200:203], v[2:5]
	v_mfma_f32_16x16x32_bf16 v[54:57], v[162:165], v[180:183], v[54:57]
	v_mfma_f32_16x16x32_bf16 v[46:49], v[170:173], v[180:183], v[46:49]
	v_mfma_f32_16x16x32_bf16 v[38:41], v[162:165], v[188:191], v[38:41]
	v_mfma_f32_16x16x32_bf16 v[30:33], v[170:173], v[188:191], v[30:33]
	v_mfma_f32_16x16x32_bf16 v[22:25], v[162:165], v[196:199], v[22:25]
	v_mfma_f32_16x16x32_bf16 v[14:17], v[170:173], v[196:199], v[14:17]
	v_mfma_f32_16x16x32_bf16 v[6:9], v[162:165], v[210:213], v[6:9]
	v_mfma_f32_16x16x32_bf16 v[2:5], v[170:173], v[210:213], v[2:5]
	s_barrier
; #define PG8_SB(B) __builtin_amdgcn_rcpf(1.f + expneg(B))
; #define PG8_SB(B) __builtin_amdgcn_rcpf(1.f + expneg(B))
; #define PG8_STAGE(bufoff, gbase, voff) do { _Pragma("unroll") for (int _i = 0; _i < 2; ++_i) \
;         __builtin_amdgcn_global_load_lds((const unsigned*)((const char*)(gbase) + (size_t)_i * qstep + (voff)[0]), (PG8_LAS unsigned*)(lds + (bufoff) + ldsw + _i * 8192), 16, 0, 0); } while (0)
; #define PG8_LDA(dst, b, h) do { _Pragma("unroll") for (int m = 0; m < 4; ++m) _Pragma("unroll") for (int k = 0; k < 2; ++k) dst[m][k] = *(const PG8_LAS bf16x8*)(lds + PG8_SA(b, h) + aoff + m * 2048 + k * 1024); } while (0)
; #define PG8_LDB(dst, b, h) do { _Pragma("unroll") for (int n = 0; n < 2; ++n) _Pragma("unroll") for (int k = 0; k < 2; ++k) dst[n][k] = *(const PG8_LAS bf16x8*)(lds + PG8_SB(b, h) + boff + n * 2048 + k * 1024); } while (0)
; #define PG8_MMA(ai, bj, At, Bt) do { __builtin_amdgcn_s_setprio(1); _Pragma("unroll") for (int m = 0; m < 4; ++m) _Pragma("unroll") for (int n = 0; n < 2; ++n) _Pragma("unroll") for (int k = 0; k < 2; ++k) \
;         acc[ai][bj][m][n] = __builtin_amdgcn_mfma_f32_16x16x32_bf16(Bt[n][k], At[m][k], acc[ai][bj][m][n], 0, 0, 0); __builtin_amdgcn_s_setprio(0); } while (0)
; #define PG8_WAIT_V89() do { if constexpr (SLIVER) PG8_WAIT_V(9); else PG8_WAIT_V(8); } while (0)
; #define PG8_LDS_S(b) do { if constexpr (SLIVER) { Sf[0] = *(const PG8_LAS bf16x8*)(lds + STAGE_BYTES + (b) * 2048 + soff0); Sf[1] = *(const PG8_LAS bf16x8*)(lds + STAGE_BYTES + (b) * 2048 + (soff0 ^ 64)); } } while (0)
; template <class Epi, class Sched, bool ALIGN_EPI = false, bool SP2 = false, bool SLIVER = false>
; __device__ __forceinline__ void gemm_phase(PG8_LAS unsigned char* lds, const Gemm g, const Sched& S, const Epi& E) {
;     ...
;             PG8_LDB(B0, 1, 0); PG8_LDB(B1, 1, 1); PG8_SCHED; PG8_LDA(At, 1, 0); PG8_STAGE(PG8_SA(0, 1), a2 + hstep, voffA); PG8_STAGE_S(0, s2);
;             PG8_WAIT_V89(); PG8_WAIT_L(0); PG8_BAR; PG8_MMA(0, 0, At, B0); PG8_MMA(0, 1, At, B1); PG8_BAR; PG8_SCHED;
;             PG8_LDA(At, 1, 1); PG8_LDS_S(1); PG8_STAGE(PG8_SB(1, 0), b3, voffB); PG8_STAGE(PG8_SB(1, 1), b3 + hstep, voffB); PG8_STAGE(PG8_SA(1, 0), a3, voffA);
;             PG8_WAIT_V89(); PG8_WAIT_L(0); PG8_BAR; PG8_MMA(1, 0, At, B0); PG8_MMA(1, 1, At, B1); PG8_MMA_S(); PG8_BAR; PG8_SCHED;
;     ...
;         if constexpr (ALIGN_EPI) { if (wr == 0) PG8_BAR; }
	s_setprio 0
	s_add_i32 s62, 0, 0x18000
	v_add_u32_e32 v144, s62, v145
	s_add_i32 s63, 0, 0x1c000
	ds_read_b128 v[136:139], v144
	ds_read_b128 v[140:143], v144 offset:1024
	ds_read_b128 v[150:153], v144 offset:2048
	ds_read_b128 v[154:157], v144 offset:3072
	v_add_u32_e32 v144, s63, v145
	ds_read_b128 v[158:161], v144
	ds_read_b128 v[162:165], v144 offset:1024
	ds_read_b128 v[166:169], v144 offset:2048
	ds_read_b128 v[170:173], v144 offset:3072
	s_mov_b32 m0, s51
	v_lshl_add_u64 v[216:217], v[214:215], 0, s[22:23]
	ds_read_b128 v[174:177], v149 offset:32768
	ds_read_b128 v[180:183], v149 offset:33792
	ds_read_b128 v[184:187], v149 offset:34816
	ds_read_b128 v[188:191], v149 offset:35840
	ds_read_b128 v[192:195], v149 offset:36864
	ds_read_b128 v[196:199], v149 offset:37888
	ds_read_b128 v[200:203], v149 offset:38912
	ds_read_b128 v[210:213], v149 offset:39936
	global_load_lds_dwordx4 v[216:217], off
	v_lshl_add_u64 v[216:217], v[214:215], 0, s[24:25]
	s_mov_b32 m0, s54
	s_nop 0
	global_load_lds_dwordx4 v[216:217], off
	s_waitcnt vmcnt(8)
	s_waitcnt lgkmcnt(0)
	s_setprio 1
	s_barrier
	v_mfma_f32_16x16x32_bf16 v[126:129], v[136:139], v[174:177], v[126:129]
	v_mfma_f32_16x16x32_bf16 v[122:125], v[150:153], v[174:177], v[122:125]
	v_mfma_f32_16x16x32_bf16 v[114:117], v[136:139], v[184:187], v[114:117]
	v_mfma_f32_16x16x32_bf16 v[106:109], v[150:153], v[184:187], v[106:109]
	v_mfma_f32_16x16x32_bf16 v[98:101], v[136:139], v[192:195], v[98:101]
	v_mfma_f32_16x16x32_bf16 v[90:93], v[150:153], v[192:195], v[90:93]
	v_mfma_f32_16x16x32_bf16 v[82:85], v[136:139], v[200:203], v[82:85]
	v_mfma_f32_16x16x32_bf16 v[74:77], v[150:153], v[200:203], v[74:77]
	v_mfma_f32_16x16x32_bf16 v[126:129], v[140:143], v[180:183], v[126:129]
	v_mfma_f32_16x16x32_bf16 v[122:125], v[154:157], v[180:183], v[122:125]
	v_mfma_f32_16x16x32_bf16 v[114:117], v[140:143], v[188:191], v[114:117]
	v_mfma_f32_16x16x32_bf16 v[106:109], v[154:157], v[188:191], v[106:109]
	v_mfma_f32_16x16x32_bf16 v[98:101], v[140:143], v[196:199], v[98:101]
	v_mfma_f32_16x16x32_bf16 v[90:93], v[154:157], v[196:199], v[90:93]
	v_mfma_f32_16x16x32_bf16 v[82:85], v[140:143], v[210:213], v[82:85]
	v_mfma_f32_16x16x32_bf16 v[74:77], v[154:157], v[210:213], v[74:77]
	v_mfma_f32_16x16x32_bf16 v[118:121], v[158:161], v[174:177], v[118:121]
	v_mfma_f32_16x16x32_bf16 v[110:113], v[166:169], v[174:177], v[110:113]
	v_mfma_f32_16x16x32_bf16 v[102:105], v[158:161], v[184:187], v[102:105]
	v_mfma_f32_16x16x32_bf16 v[94:97], v[166:169], v[184:187], v[94:97]
	v_mfma_f32_16x16x32_bf16 v[86:89], v[158:161], v[192:195], v[86:89]
	v_mfma_f32_16x16x32_bf16 v[78:81], v[166:169], v[192:195], v[78:81]
	v_mfma_f32_16x16x32_bf16 v[70:73], v[158:161], v[200:203], v[70:73]
	v_mfma_f32_16x16x32_bf16 v[66:69], v[166:169], v[200:203], v[66:69]
	v_mfma_f32_16x16x32_bf16 v[118:121], v[162:165], v[180:183], v[118:121]
	v_mfma_f32_16x16x32_bf16 v[110:113], v[170:173], v[180:183], v[110:113]
	v_mfma_f32_16x16x32_bf16 v[102:105], v[162:165], v[188:191], v[102:105]
	v_mfma_f32_16x16x32_bf16 v[94:97], v[170:173], v[188:191], v[94:97]
	v_mfma_f32_16x16x32_bf16 v[86:89], v[162:165], v[196:199], v[86:89]
	v_mfma_f32_16x16x32_bf16 v[78:81], v[170:173], v[196:199], v[78:81]
	v_mfma_f32_16x16x32_bf16 v[70:73], v[162:165], v[210:213], v[70:73]
	v_mfma_f32_16x16x32_bf16 v[66:69], v[170:173], v[210:213], v[66:69]
	s_barrier
	s_setprio 0
	s_add_i32 s62, s62, s53
	v_lshl_add_u64 v[216:217], v[146:147], 0, s[26:27]
	s_mov_b32 m0, s62
	ds_read_b128 v[174:177], v149 offset:49152
	ds_read_b128 v[180:183], v149 offset:50176
	ds_read_b128 v[184:187], v149 offset:51200
	ds_read_b128 v[188:191], v149 offset:52224
	ds_read_b128 v[192:195], v149 offset:53248
	ds_read_b128 v[196:199], v149 offset:54272
	ds_read_b128 v[200:203], v149 offset:55296
	ds_read_b128 v[210:213], v149 offset:56320
	global_load_lds_dwordx4 v[216:217], off
	v_lshl_add_u64 v[216:217], v[146:147], 0, s[28:29]
	s_add_i32 m0, s62, 0x2000
	s_add_i32 s62, s63, s53
	global_load_lds_dwordx4 v[216:217], off
	v_lshl_add_u64 v[216:217], v[146:147], 0, s[30:31]
	s_mov_b32 m0, s62
	v_lshl_add_u64 v[146:147], v[146:147], 0, s[34:35]
	global_load_lds_dwordx4 v[216:217], off
	s_add_i32 m0, s62, 0x2000
	s_nop 0
	global_load_lds_dwordx4 v[146:147], off
	v_lshl_add_u64 v[146:147], v[214:215], 0, s[26:27]
	s_mov_b32 m0, s10
	s_nop 0
	global_load_lds_dwordx4 v[146:147], off
	v_lshl_add_u64 v[146:147], v[214:215], 0, s[28:29]
	s_mov_b32 m0, s55
	s_nop 0
	global_load_lds_dwordx4 v[146:147], off
	s_waitcnt vmcnt(8)
	s_waitcnt lgkmcnt(0)
	s_setprio 1
	s_barrier
	v_mfma_f32_16x16x32_bf16 v[62:65], v[136:139], v[174:177], v[62:65]
	v_mfma_f32_16x16x32_bf16 v[58:61], v[150:153], v[174:177], v[58:61]
	v_mfma_f32_16x16x32_bf16 v[50:53], v[136:139], v[184:187], v[50:53]
	v_mfma_f32_16x16x32_bf16 v[42:45], v[150:153], v[184:187], v[42:45]
	v_mfma_f32_16x16x32_bf16 v[34:37], v[136:139], v[192:195], v[34:37]
	v_mfma_f32_16x16x32_bf16 v[26:29], v[150:153], v[192:195], v[26:29]
	v_mfma_f32_16x16x32_bf16 v[18:21], v[136:139], v[200:203], v[18:21]
	v_mfma_f32_16x16x32_bf16 v[10:13], v[150:153], v[200:203], v[10:13]
	v_mfma_f32_16x16x32_bf16 v[62:65], v[140:143], v[180:183], v[62:65]
	v_mfma_f32_16x16x32_bf16 v[58:61], v[154:157], v[180:183], v[58:61]
	v_mfma_f32_16x16x32_bf16 v[50:53], v[140:143], v[188:191], v[50:53]
	v_mfma_f32_16x16x32_bf16 v[42:45], v[154:157], v[188:191], v[42:45]
	v_mfma_f32_16x16x32_bf16 v[34:37], v[140:143], v[196:199], v[34:37]
	v_mfma_f32_16x16x32_bf16 v[26:29], v[154:157], v[196:199], v[26:29]
	v_mfma_f32_16x16x32_bf16 v[18:21], v[140:143], v[210:213], v[18:21]
	v_mfma_f32_16x16x32_bf16 v[10:13], v[154:157], v[210:213], v[10:13]
	v_mfma_f32_16x16x32_bf16 v[54:57], v[158:161], v[174:177], v[54:57]
	v_mfma_f32_16x16x32_bf16 v[46:49], v[166:169], v[174:177], v[46:49]
	v_mfma_f32_16x16x32_bf16 v[38:41], v[158:161], v[184:187], v[38:41]
	v_mfma_f32_16x16x32_bf16 v[30:33], v[166:169], v[184:187], v[30:33]
	v_mfma_f32_16x16x32_bf16 v[22:25], v[158:161], v[192:195], v[22:25]
	v_mfma_f32_16x16x32_bf16 v[14:17], v[166:169], v[192:195], v[14:17]
	v_mfma_f32_16x16x32_bf16 v[6:9], v[158:161], v[200:203], v[6:9]
	v_mfma_f32_16x16x32_bf16 v[2:5], v[166:169], v[200:203], v[2:5]
	v_mfma_f32_16x16x32_bf16 v[54:57], v[162:165], v[180:183], v[54:57]
	v_mfma_f32_16x16x32_bf16 v[46:49], v[170:173], v[180:183], v[46:49]
	v_mfma_f32_16x16x32_bf16 v[38:41], v[162:165], v[188:191], v[38:41]
	v_mfma_f32_16x16x32_bf16 v[30:33], v[170:173], v[188:191], v[30:33]
	v_mfma_f32_16x16x32_bf16 v[22:25], v[162:165], v[196:199], v[22:25]
	v_mfma_f32_16x16x32_bf16 v[14:17], v[170:173], v[196:199], v[14:17]
	v_mfma_f32_16x16x32_bf16 v[6:9], v[162:165], v[210:213], v[6:9]
	v_mfma_f32_16x16x32_bf16 v[2:5], v[170:173], v[210:213], v[2:5]
	s_barrier
	s_setprio 0
	s_add_i32 s76, s76, 2
	s_add_u32 s40, s40, 0x100
	s_addc_u32 s41, s41, 0
	s_add_u32 s68, s68, 0x100
	s_addc_u32 s69, s69, 0
	s_cmp_gt_u32 s76, 29
	s_cbranch_scc0 .LBB0_153
	s_and_b64 vcc, exec, s[48:49]
	s_cbranch_vccz .LBB0_156
	s_barrier

; #define PG8_STAGE(bufoff, gbase, voff) do { _Pragma("unroll") for (int _i = 0; _i < 2; ++_i) \
;         __builtin_amdgcn_global_load_lds((const unsigned*)((const char*)(gbase) + (size_t)_i * qstep + (voff)[0]), (PG8_LAS unsigned*)(lds + (bufoff) + ldsw + _i * 8192), 16, 0, 0); } while (0)
; #define PG8_LDA(dst, b, h) do { _Pragma("unroll") for (int m = 0; m < 4; ++m) _Pragma("unroll") for (int k = 0; k < 2; ++k) dst[m][k] = *(const PG8_LAS bf16x8*)(lds + PG8_SA(b, h) + aoff + m * 2048 + k * 1024); } while (0)
; #define PG8_LDB(dst, b, h) do { _Pragma("unroll") for (int n = 0; n < 2; ++n) _Pragma("unroll") for (int k = 0; k < 2; ++k) dst[n][k] = *(const PG8_LAS bf16x8*)(lds + PG8_SB(b, h) + boff + n * 2048 + k * 1024); } while (0)
; #define PG8_MMA(ai, bj, At, Bt) do { __builtin_amdgcn_s_setprio(1); _Pragma("unroll") for (int m = 0; m < 4; ++m) _Pragma("unroll") for (int n = 0; n < 2; ++n) _Pragma("unroll") for (int k = 0; k < 2; ++k) \
;         acc[ai][bj][m][n] = __builtin_amdgcn_mfma_f32_16x16x32_bf16(Bt[n][k], At[m][k], acc[ai][bj][m][n], 0, 0, 0); __builtin_amdgcn_s_setprio(0); } while (0)
; #define PG8_WAIT_V89() do { if constexpr (SLIVER) PG8_WAIT_V(9); else PG8_WAIT_V(8); } while (0)
; #define PG8_WAIT_L(n) asm volatile("s_waitcnt lgkmcnt(" #n ")" ::: "memory")
; #define PG8_BAR __builtin_amdgcn_s_barrier()
; #define PG8_SCHED __builtin_amdgcn_sched_barrier(0)
; template <class Epi, class Sched, bool ALIGN_EPI = false, bool SP2 = false, bool SLIVER = false>
; __device__ __forceinline__ void gemm_phase(PG8_LAS unsigned char* lds, const Gemm g, const Sched& S, const Epi& E) {
;     ...
;             const bool last = (t == nt - 2);
;             const char* a1 = cA + (size_t)(t + 1) * kstep;
;             const char* a2 = last ? nA : cA + (size_t)(t + 2) * kstep; const char* b2 = last ? nB : cB + (size_t)(t + 2) * kstep;
;             const char* a3 = a2 + kstep; const char* b3 = b2 + kstep;
;             const char* s1 = cS + (size_t)(t + 1) * kstep; const char* s2 = last ? nS : cS + (size_t)(t + 2) * kstep;
;             if (last && has_next) S.a_ready(nxt);
;             if constexpr (SP2) {
;             PG8_LDB(B0, 0, 0); PG8_LDB(B1, 0, 1); PG8_SCHED; PG8_LDA(At, 0, 0); PG8_STAGE(PG8_SA(1, 1), a1 + hstep, voffA); PG8_STAGE_S(1, s1);
;             PG8_WAIT_V89(); PG8_WAIT_L(0); PG8_BAR; PG8_MMA(0, 0, At, B0); PG8_MMA(0, 1, At, B1); PG8_BAR; PG8_SCHED;
.LBB0_498:
	s_cmp_eq_u32 s66, s80
	s_cselect_b64 s[86:87], -1, 0
	s_add_u32 s40, s16, s80
	s_addc_u32 s41, s17, s81
	s_add_u32 s68, s40, 0x100
	s_addc_u32 s69, s41, 0
	s_and_b64 s[40:41], s[86:87], exec
	s_cselect_b32 s41, s55, s69
	s_cselect_b32 s40, s54, s68
	s_add_u32 s76, s12, s80
	s_addc_u32 s77, s13, s81
	s_add_i32 s78, 0, 0x10000
	s_and_b64 s[68:69], s[86:87], exec
	v_add_u32_e32 v138, s78, v239
	s_cselect_b32 s69, s83, s77
	s_cselect_b32 s68, s82, s76
	s_add_i32 s76, 0, 0x14000
	ds_read_b128 v[146:149], v138
	ds_read_b128 v[150:153], v138 offset:1024
	ds_read_b128 v[154:157], v138 offset:2048
	ds_read_b128 v[158:161], v138 offset:3072
	v_add_u32_e32 v138, s76, v239
	ds_read_b128 v[166:169], v138
	ds_read_b128 v[170:173], v138 offset:1024
	ds_read_b128 v[174:177], v138 offset:2048
	ds_read_b128 v[162:165], v138 offset:3072
	v_lshl_add_u64 v[208:209], v[188:189], 0, s[80:81]
	v_lshl_add_u64 v[224:225], v[208:209], 0, s[34:35]
	s_add_i32 m0, s96, 0xc000
	s_mov_b64 s[88:89], 0x120080
	ds_read_b128 v[138:141], v242
	ds_read_b128 v[142:145], v242 offset:1024
	ds_read_b128 v[180:183], v242 offset:2048
	ds_read_b128 v[184:187], v242 offset:3072
	ds_read_b128 v[192:195], v242 offset:4096
	ds_read_b128 v[196:199], v242 offset:5120
	ds_read_b128 v[200:203], v242 offset:6144
	ds_read_b128 v[220:223], v242 offset:7168
	global_load_lds_dwordx4 v[224:225], off
	v_lshl_add_u64 v[208:209], v[208:209], 0, s[88:89]
	s_add_i32 m0, s96, 0xe000
	s_nop 0
	global_load_lds_dwordx4 v[208:209], off
	v_lshl_add_u64 v[208:209], v[190:191], 0, s[80:81]
	s_add_i32 m0, s94, 0x20800
	s_nop 0
	global_load_lds_dword v[208:209], off
	s_waitcnt vmcnt(9)
	s_waitcnt lgkmcnt(0)
	s_setprio 1
	s_barrier
	v_mfma_f32_16x16x32_bf16 v[134:137], v[146:149], v[138:141], v[134:137]
	v_mfma_f32_16x16x32_bf16 v[130:133], v[154:157], v[138:141], v[130:133]
	v_mfma_f32_16x16x32_bf16 v[126:129], v[146:149], v[180:183], v[126:129]
	v_mfma_f32_16x16x32_bf16 v[122:125], v[154:157], v[180:183], v[122:125]
	v_mfma_f32_16x16x32_bf16 v[118:121], v[146:149], v[192:195], v[118:121]
	v_mfma_f32_16x16x32_bf16 v[114:117], v[154:157], v[192:195], v[114:117]
	v_mfma_f32_16x16x32_bf16 v[110:113], v[146:149], v[200:203], v[110:113]
	v_mfma_f32_16x16x32_bf16 v[106:109], v[154:157], v[200:203], v[106:109]
	v_mfma_f32_16x16x32_bf16 v[134:137], v[150:153], v[142:145], v[134:137]
	v_mfma_f32_16x16x32_bf16 v[130:133], v[158:161], v[142:145], v[130:133]
	v_mfma_f32_16x16x32_bf16 v[126:129], v[150:153], v[184:187], v[126:129]
	v_mfma_f32_16x16x32_bf16 v[122:125], v[158:161], v[184:187], v[122:125]
	v_mfma_f32_16x16x32_bf16 v[118:121], v[150:153], v[196:199], v[118:121]
	v_mfma_f32_16x16x32_bf16 v[114:117], v[158:161], v[196:199], v[114:117]
	v_mfma_f32_16x16x32_bf16 v[110:113], v[150:153], v[220:223], v[110:113]
	v_mfma_f32_16x16x32_bf16 v[106:109], v[158:161], v[220:223], v[106:109]
	v_mfma_f32_16x16x32_bf16 v[102:105], v[166:169], v[138:141], v[102:105]
	v_mfma_f32_16x16x32_bf16 v[98:101], v[174:177], v[138:141], v[98:101]
	v_mfma_f32_16x16x32_bf16 v[90:93], v[166:169], v[180:183], v[90:93]
	v_mfma_f32_16x16x32_bf16 v[86:89], v[174:177], v[180:183], v[86:89]
	v_mfma_f32_16x16x32_bf16 v[78:81], v[166:169], v[192:195], v[78:81]
	v_mfma_f32_16x16x32_bf16 v[74:77], v[174:177], v[192:195], v[74:77]
	v_mfma_f32_16x16x32_bf16 v[70:73], v[166:169], v[200:203], v[70:73]
	v_mfma_f32_16x16x32_bf16 v[66:69], v[174:177], v[200:203], v[66:69]
	v_mfma_f32_16x16x32_bf16 v[102:105], v[170:173], v[142:145], v[102:105]
	v_mfma_f32_16x16x32_bf16 v[98:101], v[162:165], v[142:145], v[98:101]
	v_mfma_f32_16x16x32_bf16 v[90:93], v[170:173], v[184:187], v[90:93]
	v_mfma_f32_16x16x32_bf16 v[86:89], v[162:165], v[184:187], v[86:89]
	v_mfma_f32_16x16x32_bf16 v[78:81], v[170:173], v[196:199], v[78:81]
	v_mfma_f32_16x16x32_bf16 v[74:77], v[162:165], v[196:199], v[74:77]
	v_mfma_f32_16x16x32_bf16 v[70:73], v[170:173], v[220:223], v[70:73]
	v_mfma_f32_16x16x32_bf16 v[66:69], v[162:165], v[220:223], v[66:69]
	s_barrier
; #define PG8_SB(B) __builtin_amdgcn_rcpf(1.f + expneg(B))
; #define PG8_SB(B) __builtin_amdgcn_rcpf(1.f + expneg(B))
; #define PG8_STAGE(bufoff, gbase, voff) do { _Pragma("unroll") for (int _i = 0; _i < 2; ++_i) \
;         __builtin_amdgcn_global_load_lds((const unsigned*)((const char*)(gbase) + (size_t)_i * qstep + (voff)[0]), (PG8_LAS unsigned*)(lds + (bufoff) + ldsw + _i * 8192), 16, 0, 0); } while (0)
; #define PG8_LDA(dst, b, h) do { _Pragma("unroll") for (int m = 0; m < 4; ++m) _Pragma("unroll") for (int k = 0; k < 2; ++k) dst[m][k] = *(const PG8_LAS bf16x8*)(lds + PG8_SA(b, h) + aoff + m * 2048 + k * 1024); } while (0)
; #define PG8_MMA(ai, bj, At, Bt) do { __builtin_amdgcn_s_setprio(1); _Pragma("unroll") for (int m = 0; m < 4; ++m) _Pragma("unroll") for (int n = 0; n < 2; ++n) _Pragma("unroll") for (int k = 0; k < 2; ++k) \
;         acc[ai][bj][m][n] = __builtin_amdgcn_mfma_f32_16x16x32_bf16(Bt[n][k], At[m][k], acc[ai][bj][m][n], 0, 0, 0); __builtin_amdgcn_s_setprio(0); } while (0)
; #define PG8_WAIT_V89() do { if constexpr (SLIVER) PG8_WAIT_V(9); else PG8_WAIT_V(8); } while (0)
; #define PG8_LDS_S(b) do { if constexpr (SLIVER) { Sf[0] = *(const PG8_LAS bf16x8*)(lds + STAGE_BYTES + (b) * 2048 + soff0); Sf[1] = *(const PG8_LAS bf16x8*)(lds + STAGE_BYTES + (b) * 2048 + (soff0 ^ 64)); } } while (0)
; #define PG8_WAIT_L(n) asm volatile("s_waitcnt lgkmcnt(" #n ")" ::: "memory")
; #define PG8_BAR __builtin_amdgcn_s_barrier()
; #define PG8_SCHED __builtin_amdgcn_sched_barrier(0)
; template <class Epi, class Sched, bool ALIGN_EPI = false, bool SP2 = false, bool SLIVER = false>
; __device__ __forceinline__ void gemm_phase(PG8_LAS unsigned char* lds, const Gemm g, const Sched& S, const Epi& E) {
;     ...
;             PG8_WAIT_V89(); PG8_WAIT_L(0); PG8_BAR; PG8_MMA(0, 0, At, B0); PG8_MMA(0, 1, At, B1); PG8_BAR; PG8_SCHED;
;             PG8_LDA(At, 0, 1); PG8_LDS_S(0); PG8_STAGE(PG8_SB(0, 0), b2, voffB); PG8_STAGE(PG8_SB(0, 1), b2 + hstep, voffB); PG8_STAGE(PG8_SA(0, 0), a2, voffA);
;             PG8_WAIT_V89(); PG8_WAIT_L(0); PG8_BAR; PG8_MMA(1, 0, At, B0); PG8_MMA(1, 1, At, B1); PG8_MMA_S(); PG8_BAR; PG8_SCHED;
	s_setprio 0
	s_add_i32 s77, 0, 0x20000
	v_lshl_add_u64 v[192:193], s[68:69], 0, v[212:213]
	s_add_i32 s68, s78, s95
	v_add_u32_e32 v178, s77, v240
	v_add_u32_e32 v184, s77, v241
	s_mov_b32 m0, s68
	s_mov_b64 s[88:89], 0x60000
	ds_read_b128 v[138:141], v242 offset:16384
	ds_read_b128 v[142:145], v242 offset:17408
	ds_read_b128 v[196:199], v242 offset:18432
	ds_read_b128 v[200:203], v242 offset:19456
	ds_read_b128 v[220:223], v242 offset:20480
	ds_read_b128 v[224:227], v242 offset:21504
	ds_read_b128 v[228:231], v242 offset:22528
	ds_read_b128 v[232:235], v242 offset:23552
	ds_read_b128 v[180:183], v178
	ds_read_b128 v[184:187], v184
	global_load_lds_dwordx4 v[192:193], off
	v_lshl_add_u64 v[194:195], v[192:193], 0, s[88:89]
	s_add_i32 m0, s68, 0x2000
	s_add_i32 s68, s76, s95
	global_load_lds_dwordx4 v[194:195], off
	v_lshl_add_u64 v[194:195], v[192:193], 0, s[24:25]
	s_mov_b32 m0, s68
	s_nop 0
	global_load_lds_dwordx4 v[194:195], off
	v_lshl_add_u64 v[194:195], v[192:193], 0, s[14:15]
	s_add_i32 m0, s68, 0x2000
	s_nop 0
	global_load_lds_dwordx4 v[194:195], off
	v_lshl_add_u64 v[194:195], s[40:41], 0, v[210:211]
	s_mov_b32 m0, s96
	v_lshl_add_u64 v[208:209], v[194:195], 0, s[88:89]
	global_load_lds_dwordx4 v[194:195], off
	s_mov_b32 m0, s19
	s_nop 0
	global_load_lds_dwordx4 v[208:209], off
	s_waitcnt vmcnt(9)
	s_waitcnt lgkmcnt(0)
	s_setprio 1
	s_barrier
	v_mfma_f32_16x16x32_bf16 v[62:65], v[146:149], v[138:141], v[62:65]
	v_mfma_f32_16x16x32_bf16 v[58:61], v[154:157], v[138:141], v[58:61]
	v_mfma_f32_16x16x32_bf16 v[54:57], v[146:149], v[196:199], v[54:57]
	v_mfma_f32_16x16x32_bf16 v[50:53], v[154:157], v[196:199], v[50:53]
	v_mfma_f32_16x16x32_bf16 v[46:49], v[146:149], v[220:223], v[46:49]
	v_mfma_f32_16x16x32_bf16 v[42:45], v[154:157], v[220:223], v[42:45]
	v_mfma_f32_16x16x32_bf16 v[38:41], v[146:149], v[228:231], v[38:41]
	v_mfma_f32_16x16x32_bf16 v[34:37], v[154:157], v[228:231], v[34:37]
	v_mfma_f32_16x16x32_bf16 v[62:65], v[150:153], v[142:145], v[62:65]
	v_mfma_f32_16x16x32_bf16 v[58:61], v[158:161], v[142:145], v[58:61]
	v_mfma_f32_16x16x32_bf16 v[54:57], v[150:153], v[200:203], v[54:57]
	v_mfma_f32_16x16x32_bf16 v[50:53], v[158:161], v[200:203], v[50:53]
	v_mfma_f32_16x16x32_bf16 v[46:49], v[150:153], v[224:227], v[46:49]
	v_mfma_f32_16x16x32_bf16 v[42:45], v[158:161], v[224:227], v[42:45]
	v_mfma_f32_16x16x32_bf16 v[38:41], v[150:153], v[232:235], v[38:41]
	v_mfma_f32_16x16x32_bf16 v[34:37], v[158:161], v[232:235], v[34:37]
	v_mfma_f32_16x16x32_bf16 v[30:33], v[166:169], v[138:141], v[30:33]
	v_mfma_f32_16x16x32_bf16 v[26:29], v[174:177], v[138:141], v[26:29]
	v_mfma_f32_16x16x32_bf16 v[22:25], v[166:169], v[196:199], v[22:25]
	v_mfma_f32_16x16x32_bf16 v[18:21], v[174:177], v[196:199], v[18:21]
	v_mfma_f32_16x16x32_bf16 v[14:17], v[166:169], v[220:223], v[14:17]
	v_mfma_f32_16x16x32_bf16 v[10:13], v[174:177], v[220:223], v[10:13]
	v_mfma_f32_16x16x32_bf16 v[6:9], v[166:169], v[228:231], v[6:9]
	v_mfma_f32_16x16x32_bf16 v[2:5], v[174:177], v[228:231], v[2:5]
	v_mfma_f32_16x16x32_bf16 v[30:33], v[170:173], v[142:145], v[30:33]
	v_mfma_f32_16x16x32_bf16 v[26:29], v[162:165], v[142:145], v[26:29]
	v_mfma_f32_16x16x32_bf16 v[22:25], v[170:173], v[200:203], v[22:25]
	v_mfma_f32_16x16x32_bf16 v[18:21], v[162:165], v[200:203], v[18:21]
	v_mfma_f32_16x16x32_bf16 v[14:17], v[170:173], v[224:227], v[14:17]
	v_mfma_f32_16x16x32_bf16 v[10:13], v[162:165], v[224:227], v[10:13]
	v_mfma_f32_16x16x32_bf16 v[6:9], v[170:173], v[232:235], v[6:9]
	v_mfma_f32_16x16x32_bf16 v[2:5], v[162:165], v[232:235], v[2:5]
	s_setprio 0
	s_setprio 1
	v_cndmask_b32_e64 v138, 0, 1, s[52:53]
	v_cmp_ne_u32_e64 s[40:41], 1, v138
	s_andn2_b64 vcc, exec, s[52:53]
	s_mov_b64 s[88:89], -1
	s_cbranch_vccnz .LBB0_500
	v_mfma_f32_16x16x32_bf16 v[138:141], v[166:169], v[180:183], v[82:85]
	s_mov_b64 s[88:89], 0
	v_mfma_f32_16x16x32_bf16 v[142:145], v[174:177], v[180:183], v[94:97]
	v_mfma_f32_16x16x32_bf16 v[138:141], v[170:173], v[184:187], v[138:141]
	v_mfma_f32_16x16x32_bf16 v[142:145], v[162:165], v[184:187], v[142:145]

; #define PG8_SB(B) __builtin_amdgcn_rcpf(1.f + expneg(B))
; #define PG8_SB(B) __builtin_amdgcn_rcpf(1.f + expneg(B))
; #define PG8_STAGE(bufoff, gbase, voff) do { _Pragma("unroll") for (int _i = 0; _i < 2; ++_i) \
;         __builtin_amdgcn_global_load_lds((const unsigned*)((const char*)(gbase) + (size_t)_i * qstep + (voff)[0]), (PG8_LAS unsigned*)(lds + (bufoff) + ldsw + _i * 8192), 16, 0, 0); } while (0)
; #define PG8_LDA(dst, b, h) do { _Pragma("unroll") for (int m = 0; m < 4; ++m) _Pragma("unroll") for (int k = 0; k < 2; ++k) dst[m][k] = *(const PG8_LAS bf16x8*)(lds + PG8_SA(b, h) + aoff + m * 2048 + k * 1024); } while (0)
; #define PG8_LDB(dst, b, h) do { _Pragma("unroll") for (int n = 0; n < 2; ++n) _Pragma("unroll") for (int k = 0; k < 2; ++k) dst[n][k] = *(const PG8_LAS bf16x8*)(lds + PG8_SB(b, h) + boff + n * 2048 + k * 1024); } while (0)
; #define PG8_WAIT_L(n) asm volatile("s_waitcnt lgkmcnt(" #n ")" ::: "memory")
; template <class Epi, class Sched, bool ALIGN_EPI = false, bool SP2 = false, bool SLIVER = false>
; __device__ __forceinline__ void gemm_phase(PG8_LAS unsigned char* lds, const Gemm g, const Sched& S, const Epi& E) {
;     ...
;             const char* a2 = last ? nA : cA + (size_t)(t + 2) * kstep; const char* b2 = last ? nB : cB + (size_t)(t + 2) * kstep;
;             const char* a3 = a2 + kstep; const char* b3 = b2 + kstep;
;             const char* s1 = cS + (size_t)(t + 1) * kstep; const char* s2 = last ? nS : cS + (size_t)(t + 2) * kstep;
;             if (last && has_next) S.a_ready(nxt);
;             if constexpr (SP2) {
;             PG8_LDB(B0, 0, 0); PG8_LDB(B1, 0, 1); PG8_SCHED; PG8_LDA(At, 0, 0); PG8_STAGE(PG8_SA(1, 1), a1 + hstep, voffA); PG8_STAGE_S(1, s1);
;             PG8_WAIT_V89(); PG8_WAIT_L(0); PG8_BAR; PG8_MMA(0, 0, At, B0); PG8_MMA(0, 1, At, B1); PG8_BAR; PG8_SCHED;
;             PG8_LDA(At, 0, 1); PG8_LDS_S(0); PG8_STAGE(PG8_SB(0, 0), b2, voffB); PG8_STAGE(PG8_SB(0, 1), b2 + hstep, voffB); PG8_STAGE(PG8_SA(0, 0), a2, voffA);
;             PG8_WAIT_V89(); PG8_WAIT_L(0); PG8_BAR; PG8_MMA(1, 0, At, B0); PG8_MMA(1, 1, At, B1); PG8_MMA_S(); PG8_BAR; PG8_SCHED;
;             PG8_LDB(B0, 1, 0); PG8_LDB(B1, 1, 1); PG8_SCHED; PG8_LDA(At, 1, 0); PG8_STAGE(PG8_SA(0, 1), a2 + hstep, voffA); PG8_STAGE_S(0, s2);
;             PG8_WAIT_V89(); PG8_WAIT_L(0); PG8_BAR; PG8_MMA(0, 0, At, B0); PG8_MMA(0, 1, At, B1); PG8_BAR; PG8_SCHED;
.LBB0_502:
	s_add_u32 s68, s62, s80
	s_addc_u32 s69, s63, s81
	s_add_u32 s76, s68, 0x100
	s_addc_u32 s77, s69, 0
	s_and_b64 s[68:69], s[86:87], exec
	s_cselect_b32 s69, s85, s77
	s_cselect_b32 s68, s84, s76
	s_barrier
	s_setprio 0
	s_add_i32 s76, 0, 0x18000
	v_add_u32_e32 v82, s76, v239
	s_add_i32 s77, 0, 0x1c000
	ds_read_b128 v[146:149], v82
	ds_read_b128 v[150:153], v82 offset:1024
	ds_read_b128 v[154:157], v82 offset:2048
	ds_read_b128 v[158:161], v82 offset:3072
	v_add_u32_e32 v82, s77, v239
	ds_read_b128 v[166:169], v82
	ds_read_b128 v[170:173], v82 offset:1024
	ds_read_b128 v[174:177], v82 offset:2048
	ds_read_b128 v[162:165], v82 offset:3072
	s_mov_b32 m0, s91
	v_lshl_add_u64 v[208:209], v[194:195], 0, s[24:25]
	ds_read_b128 v[82:85], v242 offset:32768
	ds_read_b128 v[94:97], v242 offset:33792
	ds_read_b128 v[180:183], v242 offset:34816
	ds_read_b128 v[184:187], v242 offset:35840
	ds_read_b128 v[196:199], v242 offset:36864
	ds_read_b128 v[200:203], v242 offset:37888
	ds_read_b128 v[220:223], v242 offset:38912
	ds_read_b128 v[224:227], v242 offset:39936
	global_load_lds_dwordx4 v[208:209], off
	v_lshl_add_u64 v[208:209], v[194:195], 0, s[14:15]
	s_mov_b32 m0, s92
	s_nop 0
	global_load_lds_dwordx4 v[208:209], off
	v_lshl_add_u64 v[208:209], s[68:69], 0, v[214:215]
	s_mov_b32 m0, s93
	s_nop 0
	global_load_lds_dword v[208:209], off
	s_waitcnt vmcnt(9)
	s_waitcnt lgkmcnt(0)
	s_setprio 1
	s_barrier
	v_mfma_f32_16x16x32_bf16 v[134:137], v[146:149], v[82:85], v[134:137]
	v_mfma_f32_16x16x32_bf16 v[130:133], v[154:157], v[82:85], v[130:133]
	v_mfma_f32_16x16x32_bf16 v[126:129], v[146:149], v[180:183], v[126:129]
	v_mfma_f32_16x16x32_bf16 v[122:125], v[154:157], v[180:183], v[122:125]
	v_mfma_f32_16x16x32_bf16 v[118:121], v[146:149], v[196:199], v[118:121]
	v_mfma_f32_16x16x32_bf16 v[114:117], v[154:157], v[196:199], v[114:117]
	v_mfma_f32_16x16x32_bf16 v[110:113], v[146:149], v[220:223], v[110:113]
	v_mfma_f32_16x16x32_bf16 v[106:109], v[154:157], v[220:223], v[106:109]
	v_mfma_f32_16x16x32_bf16 v[134:137], v[150:153], v[94:97], v[134:137]
	v_mfma_f32_16x16x32_bf16 v[130:133], v[158:161], v[94:97], v[130:133]
	v_mfma_f32_16x16x32_bf16 v[126:129], v[150:153], v[184:187], v[126:129]
	v_mfma_f32_16x16x32_bf16 v[122:125], v[158:161], v[184:187], v[122:125]
	v_mfma_f32_16x16x32_bf16 v[118:121], v[150:153], v[200:203], v[118:121]
	v_mfma_f32_16x16x32_bf16 v[114:117], v[158:161], v[200:203], v[114:117]
	v_mfma_f32_16x16x32_bf16 v[110:113], v[150:153], v[224:227], v[110:113]
	v_mfma_f32_16x16x32_bf16 v[106:109], v[158:161], v[224:227], v[106:109]
	v_mfma_f32_16x16x32_bf16 v[102:105], v[166:169], v[82:85], v[102:105]
	v_mfma_f32_16x16x32_bf16 v[82:85], v[174:177], v[82:85], v[98:101]
	v_mfma_f32_16x16x32_bf16 v[98:101], v[162:165], v[94:97], v[82:85]
	v_mfma_f32_16x16x32_bf16 v[82:85], v[166:169], v[180:183], v[90:93]
	v_mfma_f32_16x16x32_bf16 v[90:93], v[170:173], v[184:187], v[82:85]
	v_mfma_f32_16x16x32_bf16 v[82:85], v[174:177], v[180:183], v[86:89]
	v_mfma_f32_16x16x32_bf16 v[78:81], v[166:169], v[196:199], v[78:81]
	v_mfma_f32_16x16x32_bf16 v[74:77], v[174:177], v[196:199], v[74:77]
	v_mfma_f32_16x16x32_bf16 v[70:73], v[166:169], v[220:223], v[70:73]
	v_mfma_f32_16x16x32_bf16 v[66:69], v[174:177], v[220:223], v[66:69]
	v_mfma_f32_16x16x32_bf16 v[102:105], v[170:173], v[94:97], v[102:105]
	v_mfma_f32_16x16x32_bf16 v[86:89], v[162:165], v[184:187], v[82:85]
	v_mfma_f32_16x16x32_bf16 v[78:81], v[170:173], v[200:203], v[78:81]
	v_mfma_f32_16x16x32_bf16 v[74:77], v[162:165], v[200:203], v[74:77]
	v_mfma_f32_16x16x32_bf16 v[70:73], v[170:173], v[224:227], v[70:73]
	v_mfma_f32_16x16x32_bf16 v[66:69], v[162:165], v[224:227], v[66:69]
	s_barrier
; #define PG8_SB(B) __builtin_amdgcn_rcpf(1.f + expneg(B))
; #define PG8_SB(B) __builtin_amdgcn_rcpf(1.f + expneg(B))
; #define PG8_STAGE(bufoff, gbase, voff) do { _Pragma("unroll") for (int _i = 0; _i < 2; ++_i) \
;         __builtin_amdgcn_global_load_lds((const unsigned*)((const char*)(gbase) + (size_t)_i * qstep + (voff)[0]), (PG8_LAS unsigned*)(lds + (bufoff) + ldsw + _i * 8192), 16, 0, 0); } while (0)
; #define PG8_LDA(dst, b, h) do { _Pragma("unroll") for (int m = 0; m < 4; ++m) _Pragma("unroll") for (int k = 0; k < 2; ++k) dst[m][k] = *(const PG8_LAS bf16x8*)(lds + PG8_SA(b, h) + aoff + m * 2048 + k * 1024); } while (0)
; #define PG8_MMA(ai, bj, At, Bt) do { __builtin_amdgcn_s_setprio(1); _Pragma("unroll") for (int m = 0; m < 4; ++m) _Pragma("unroll") for (int n = 0; n < 2; ++n) _Pragma("unroll") for (int k = 0; k < 2; ++k) \
;         acc[ai][bj][m][n] = __builtin_amdgcn_mfma_f32_16x16x32_bf16(Bt[n][k], At[m][k], acc[ai][bj][m][n], 0, 0, 0); __builtin_amdgcn_s_setprio(0); } while (0)
; #define PG8_WAIT_V89() do { if constexpr (SLIVER) PG8_WAIT_V(9); else PG8_WAIT_V(8); } while (0)
; #define PG8_LDS_S(b) do { if constexpr (SLIVER) { Sf[0] = *(const PG8_LAS bf16x8*)(lds + STAGE_BYTES + (b) * 2048 + soff0); Sf[1] = *(const PG8_LAS bf16x8*)(lds + STAGE_BYTES + (b) * 2048 + (soff0 ^ 64)); } } while (0)
; #define PG8_WAIT_L(n) asm volatile("s_waitcnt lgkmcnt(" #n ")" ::: "memory")
; #define PG8_BAR __builtin_amdgcn_s_barrier()
; #define PG8_SCHED __builtin_amdgcn_sched_barrier(0)
; template <class Epi, class Sched, bool ALIGN_EPI = false, bool SP2 = false, bool SLIVER = false>
; __device__ __forceinline__ void gemm_phase(PG8_LAS unsigned char* lds, const Gemm g, const Sched& S, const Epi& E) {
;     ...
;             PG8_LDA(At, 1, 1); PG8_LDS_S(1); PG8_STAGE(PG8_SB(1, 0), b3, voffB); PG8_STAGE(PG8_SB(1, 1), b3 + hstep, voffB); PG8_STAGE(PG8_SA(1, 0), a3, voffA);
;             PG8_WAIT_V89(); PG8_WAIT_L(0); PG8_BAR; PG8_MMA(1, 0, At, B0); PG8_MMA(1, 1, At, B1); PG8_MMA_S(); PG8_BAR; PG8_SCHED;
	s_setprio 0
	s_add_i32 s68, 0, 0x20800
	v_add_u32_e32 v178, s68, v240
	v_add_u32_e32 v184, s68, v241
	s_add_i32 s68, s76, s95
	v_lshl_add_u64 v[208:209], v[192:193], 0, s[26:27]
	s_mov_b32 m0, s68
	ds_read_b128 v[82:85], v242 offset:49152
	ds_read_b128 v[94:97], v242 offset:50176
	ds_read_b128 v[196:199], v242 offset:51200
	ds_read_b128 v[200:203], v242 offset:52224
	ds_read_b128 v[220:223], v242 offset:53248
	ds_read_b128 v[224:227], v242 offset:54272
	ds_read_b128 v[228:231], v242 offset:55296
	ds_read_b128 v[232:235], v242 offset:56320
	ds_read_b128 v[180:183], v178
	ds_read_b128 v[184:187], v184
	global_load_lds_dwordx4 v[208:209], off
	v_lshl_add_u64 v[208:209], v[192:193], 0, s[72:73]
	s_add_i32 m0, s68, 0x2000
	s_add_i32 s68, s77, s95
	global_load_lds_dwordx4 v[208:209], off
	v_lshl_add_u64 v[208:209], v[192:193], 0, s[34:35]
	s_mov_b32 m0, s68
	s_mov_b64 s[76:77], 0x120080
	global_load_lds_dwordx4 v[208:209], off
	v_lshl_add_u64 v[192:193], v[192:193], 0, s[76:77]
	s_add_i32 m0, s68, 0x2000
	s_nop 0
	global_load_lds_dwordx4 v[192:193], off
	v_lshl_add_u64 v[192:193], v[194:195], 0, s[26:27]
	s_mov_b32 m0, s97
	s_nop 0
	global_load_lds_dwordx4 v[192:193], off
	v_lshl_add_u64 v[192:193], v[194:195], 0, s[72:73]
	s_mov_b32 m0, s18
	s_nop 0
	global_load_lds_dwordx4 v[192:193], off
	s_waitcnt vmcnt(9)
	s_waitcnt lgkmcnt(0)
	s_setprio 1
	s_barrier
	v_mfma_f32_16x16x32_bf16 v[62:65], v[146:149], v[82:85], v[62:65]
	v_mfma_f32_16x16x32_bf16 v[58:61], v[154:157], v[82:85], v[58:61]
	v_mfma_f32_16x16x32_bf16 v[54:57], v[146:149], v[196:199], v[54:57]
	v_mfma_f32_16x16x32_bf16 v[50:53], v[154:157], v[196:199], v[50:53]
	v_mfma_f32_16x16x32_bf16 v[46:49], v[146:149], v[220:223], v[46:49]
	v_mfma_f32_16x16x32_bf16 v[42:45], v[154:157], v[220:223], v[42:45]
	v_mfma_f32_16x16x32_bf16 v[38:41], v[146:149], v[228:231], v[38:41]
	v_mfma_f32_16x16x32_bf16 v[34:37], v[154:157], v[228:231], v[34:37]
	v_mfma_f32_16x16x32_bf16 v[62:65], v[150:153], v[94:97], v[62:65]
	v_mfma_f32_16x16x32_bf16 v[58:61], v[158:161], v[94:97], v[58:61]
	v_mfma_f32_16x16x32_bf16 v[54:57], v[150:153], v[200:203], v[54:57]
	v_mfma_f32_16x16x32_bf16 v[50:53], v[158:161], v[200:203], v[50:53]
	v_mfma_f32_16x16x32_bf16 v[46:49], v[150:153], v[224:227], v[46:49]
	v_mfma_f32_16x16x32_bf16 v[42:45], v[158:161], v[224:227], v[42:45]
	v_mfma_f32_16x16x32_bf16 v[38:41], v[150:153], v[232:235], v[38:41]
	v_mfma_f32_16x16x32_bf16 v[34:37], v[158:161], v[232:235], v[34:37]
	v_mfma_f32_16x16x32_bf16 v[30:33], v[166:169], v[82:85], v[30:33]
	v_mfma_f32_16x16x32_bf16 v[26:29], v[174:177], v[82:85], v[26:29]
	v_mfma_f32_16x16x32_bf16 v[22:25], v[166:169], v[196:199], v[22:25]
	v_mfma_f32_16x16x32_bf16 v[18:21], v[174:177], v[196:199], v[18:21]
	v_mfma_f32_16x16x32_bf16 v[14:17], v[166:169], v[220:223], v[14:17]
	v_mfma_f32_16x16x32_bf16 v[10:13], v[174:177], v[220:223], v[10:13]
	v_mfma_f32_16x16x32_bf16 v[6:9], v[166:169], v[228:231], v[6:9]
	v_mfma_f32_16x16x32_bf16 v[2:5], v[174:177], v[228:231], v[2:5]
	v_mfma_f32_16x16x32_bf16 v[30:33], v[170:173], v[94:97], v[30:33]
	v_mfma_f32_16x16x32_bf16 v[26:29], v[162:165], v[94:97], v[26:29]
	v_mfma_f32_16x16x32_bf16 v[22:25], v[170:173], v[200:203], v[22:25]
	v_mfma_f32_16x16x32_bf16 v[18:21], v[162:165], v[200:203], v[18:21]
	v_mfma_f32_16x16x32_bf16 v[14:17], v[170:173], v[224:227], v[14:17]
	v_mfma_f32_16x16x32_bf16 v[10:13], v[162:165], v[224:227], v[10:13]
	v_mfma_f32_16x16x32_bf16 v[6:9], v[170:173], v[232:235], v[6:9]
	v_mfma_f32_16x16x32_bf16 v[2:5], v[162:165], v[232:235], v[2:5]
	s_setprio 0
	s_setprio 1
	s_and_b64 vcc, exec, s[40:41]
	s_mov_b64 s[40:41], -1
	s_mov_b64 s[86:87], 0x4000400
	s_mov_b64 s[88:89], 0x4000800
	s_cbranch_vccnz .LBB0_504
	v_mfma_f32_16x16x32_bf16 v[82:85], v[166:169], v[180:183], v[138:141]
	s_mov_b64 s[40:41], 0
	v_mfma_f32_16x16x32_bf16 v[94:97], v[174:177], v[180:183], v[142:145]
	v_mfma_f32_16x16x32_bf16 v[82:85], v[170:173], v[184:187], v[82:85]
	v_mfma_f32_16x16x32_bf16 v[94:97], v[162:165], v[184:187], v[94:97]

; #define PG8_STAGE(bufoff, gbase, voff) do { _Pragma("unroll") for (int _i = 0; _i < 2; ++_i) \
;         __builtin_amdgcn_global_load_lds((const unsigned*)((const char*)(gbase) + (size_t)_i * qstep + (voff)[0]), (PG8_LAS unsigned*)(lds + (bufoff) + ldsw + _i * 8192), 16, 0, 0); } while (0)
; #define PG8_LDA(dst, b, h) do { _Pragma("unroll") for (int m = 0; m < 4; ++m) _Pragma("unroll") for (int k = 0; k < 2; ++k) dst[m][k] = *(const PG8_LAS bf16x8*)(lds + PG8_SA(b, h) + aoff + m * 2048 + k * 1024); } while (0)
; #define PG8_LDB(dst, b, h) do { _Pragma("unroll") for (int n = 0; n < 2; ++n) _Pragma("unroll") for (int k = 0; k < 2; ++k) dst[n][k] = *(const PG8_LAS bf16x8*)(lds + PG8_SB(b, h) + boff + n * 2048 + k * 1024); } while (0)
; #define PG8_MMA(ai, bj, At, Bt) do { __builtin_amdgcn_s_setprio(1); _Pragma("unroll") for (int m = 0; m < 4; ++m) _Pragma("unroll") for (int n = 0; n < 2; ++n) _Pragma("unroll") for (int k = 0; k < 2; ++k) \
;         acc[ai][bj][m][n] = __builtin_amdgcn_mfma_f32_16x16x32_bf16(Bt[n][k], At[m][k], acc[ai][bj][m][n], 0, 0, 0); __builtin_amdgcn_s_setprio(0); } while (0)
; #define PG8_WAIT_V89() do { if constexpr (SLIVER) PG8_WAIT_V(9); else PG8_WAIT_V(8); } while (0)
; #define PG8_WAIT_L(n) asm volatile("s_waitcnt lgkmcnt(" #n ")" ::: "memory")
; #define PG8_BAR __builtin_amdgcn_s_barrier()
; #define PG8_SCHED __builtin_amdgcn_sched_barrier(0)
; template <class Epi, class Sched, bool ALIGN_EPI = false, bool SP2 = false, bool SLIVER = false>
; __device__ __forceinline__ void gemm_phase(PG8_LAS unsigned char* lds, const Gemm g, const Sched& S, const Epi& E) {
;     ...
;             const bool last = (t == nt - 2);
;             const char* a1 = cA + (size_t)(t + 1) * kstep;
;             const char* a2 = last ? nA : cA + (size_t)(t + 2) * kstep; const char* b2 = last ? nB : cB + (size_t)(t + 2) * kstep;
;             const char* a3 = a2 + kstep; const char* b3 = b2 + kstep;
;             const char* s1 = cS + (size_t)(t + 1) * kstep; const char* s2 = last ? nS : cS + (size_t)(t + 2) * kstep;
;             if (last && has_next) S.a_ready(nxt);
;             if constexpr (SP2) {
;             PG8_LDB(B0, 0, 0); PG8_LDB(B1, 0, 1); PG8_SCHED; PG8_LDA(At, 0, 0); PG8_STAGE(PG8_SA(1, 1), a1 + hstep, voffA); PG8_STAGE_S(1, s1);
;             PG8_WAIT_V89(); PG8_WAIT_L(0); PG8_BAR; PG8_MMA(0, 0, At, B0); PG8_MMA(0, 1, At, B1); PG8_BAR; PG8_SCHED;
.LBB0_598:
	s_add_u32 s40, s92, s62
	s_addc_u32 s41, s93, s63
	s_add_u32 s77, s40, 0x100
	s_addc_u32 s78, s41, 0
	s_add_u32 s83, s68, s62
	s_addc_u32 s79, s69, s63
	s_add_i32 s96, 0, 0x10000
	s_cmpk_eq_i32 s62, 0xf00
	s_cselect_b64 s[80:81], -1, 0
	s_and_b64 s[40:41], s[80:81], exec
	s_cselect_b32 s41, s12, s78
	s_cselect_b32 s40, s13, s77
	v_add_u32_e32 v138, s96, v212
	s_cselect_b32 s79, s17, s79
	s_cselect_b32 s78, s55, s83
	s_add_i32 s77, 0, 0x14000
	ds_read_b128 v[146:149], v138
	ds_read_b128 v[150:153], v138 offset:1024
	ds_read_b128 v[154:157], v138 offset:2048
	ds_read_b128 v[158:161], v138 offset:3072
	v_add_u32_e32 v138, s77, v212
	ds_read_b128 v[166:169], v138
	ds_read_b128 v[170:173], v138 offset:1024
	ds_read_b128 v[174:177], v138 offset:2048
	ds_read_b128 v[162:165], v138 offset:3072
	v_lshl_add_u64 v[202:203], v[200:201], 0, s[62:63]
	v_lshl_add_u64 v[208:209], v[202:203], 0, s[30:31]
	s_add_i32 m0, s85, 0xc000
	ds_read_b128 v[138:141], v215
	ds_read_b128 v[142:145], v215 offset:1024
	ds_read_b128 v[180:183], v215 offset:2048
	ds_read_b128 v[184:187], v215 offset:3072
	ds_read_b128 v[216:219], v215 offset:4096
	ds_read_b128 v[220:223], v215 offset:5120
	ds_read_b128 v[224:227], v215 offset:6144
	ds_read_b128 v[228:231], v215 offset:7168
	global_load_lds_dwordx4 v[208:209], off
	v_lshl_add_u64 v[202:203], v[202:203], 0, s[34:35]
	s_add_i32 m0, s85, 0xe000
	s_nop 0
	global_load_lds_dwordx4 v[202:203], off
	v_lshl_add_u64 v[202:203], v[198:199], 0, s[62:63]
	s_add_i32 m0, s45, 0x20800
	s_nop 0
	global_load_lds_dword v[202:203], off
	s_waitcnt vmcnt(9)
	s_waitcnt lgkmcnt(0)
	s_setprio 1
	s_barrier
	v_mfma_f32_16x16x32_bf16 v[134:137], v[146:149], v[138:141], v[134:137]
	v_mfma_f32_16x16x32_bf16 v[130:133], v[154:157], v[138:141], v[130:133]
	v_mfma_f32_16x16x32_bf16 v[118:121], v[146:149], v[180:183], v[118:121]
	v_mfma_f32_16x16x32_bf16 v[114:117], v[154:157], v[180:183], v[114:117]
	v_mfma_f32_16x16x32_bf16 v[102:105], v[146:149], v[216:219], v[102:105]
	v_mfma_f32_16x16x32_bf16 v[98:101], v[154:157], v[216:219], v[98:101]
	v_mfma_f32_16x16x32_bf16 v[86:89], v[146:149], v[224:227], v[86:89]
	v_mfma_f32_16x16x32_bf16 v[82:85], v[154:157], v[224:227], v[82:85]
	v_mfma_f32_16x16x32_bf16 v[134:137], v[150:153], v[142:145], v[134:137]
	v_mfma_f32_16x16x32_bf16 v[130:133], v[158:161], v[142:145], v[130:133]
	v_mfma_f32_16x16x32_bf16 v[118:121], v[150:153], v[184:187], v[118:121]
	v_mfma_f32_16x16x32_bf16 v[114:117], v[158:161], v[184:187], v[114:117]
	v_mfma_f32_16x16x32_bf16 v[102:105], v[150:153], v[220:223], v[102:105]
	v_mfma_f32_16x16x32_bf16 v[98:101], v[158:161], v[220:223], v[98:101]
	v_mfma_f32_16x16x32_bf16 v[86:89], v[150:153], v[228:231], v[86:89]
	v_mfma_f32_16x16x32_bf16 v[82:85], v[158:161], v[228:231], v[82:85]
	v_mfma_f32_16x16x32_bf16 v[126:129], v[166:169], v[138:141], v[126:129]
	v_mfma_f32_16x16x32_bf16 v[122:125], v[174:177], v[138:141], v[122:125]
	v_mfma_f32_16x16x32_bf16 v[110:113], v[166:169], v[180:183], v[110:113]
	v_mfma_f32_16x16x32_bf16 v[106:109], v[174:177], v[180:183], v[106:109]
	v_mfma_f32_16x16x32_bf16 v[94:97], v[166:169], v[216:219], v[94:97]
	v_mfma_f32_16x16x32_bf16 v[90:93], v[174:177], v[216:219], v[90:93]
	v_mfma_f32_16x16x32_bf16 v[78:81], v[166:169], v[224:227], v[78:81]
	v_mfma_f32_16x16x32_bf16 v[74:77], v[174:177], v[224:227], v[74:77]
	v_mfma_f32_16x16x32_bf16 v[126:129], v[170:173], v[142:145], v[126:129]
	v_mfma_f32_16x16x32_bf16 v[122:125], v[162:165], v[142:145], v[122:125]
	v_mfma_f32_16x16x32_bf16 v[110:113], v[170:173], v[184:187], v[110:113]
	v_mfma_f32_16x16x32_bf16 v[106:109], v[162:165], v[184:187], v[106:109]
	v_mfma_f32_16x16x32_bf16 v[94:97], v[170:173], v[220:223], v[94:97]
	v_mfma_f32_16x16x32_bf16 v[90:93], v[162:165], v[220:223], v[90:93]
	v_mfma_f32_16x16x32_bf16 v[78:81], v[170:173], v[228:231], v[78:81]
	v_mfma_f32_16x16x32_bf16 v[74:77], v[162:165], v[228:231], v[74:77]
	s_barrier
; #define PG8_SB(B) __builtin_amdgcn_rcpf(1.f + expneg(B))
; #define PG8_SB(B) __builtin_amdgcn_rcpf(1.f + expneg(B))
; #define PG8_STAGE(bufoff, gbase, voff) do { _Pragma("unroll") for (int _i = 0; _i < 2; ++_i) \
;         __builtin_amdgcn_global_load_lds((const unsigned*)((const char*)(gbase) + (size_t)_i * qstep + (voff)[0]), (PG8_LAS unsigned*)(lds + (bufoff) + ldsw + _i * 8192), 16, 0, 0); } while (0)
; #define PG8_LDA(dst, b, h) do { _Pragma("unroll") for (int m = 0; m < 4; ++m) _Pragma("unroll") for (int k = 0; k < 2; ++k) dst[m][k] = *(const PG8_LAS bf16x8*)(lds + PG8_SA(b, h) + aoff + m * 2048 + k * 1024); } while (0)
; #define PG8_MMA(ai, bj, At, Bt) do { __builtin_amdgcn_s_setprio(1); _Pragma("unroll") for (int m = 0; m < 4; ++m) _Pragma("unroll") for (int n = 0; n < 2; ++n) _Pragma("unroll") for (int k = 0; k < 2; ++k) \
;         acc[ai][bj][m][n] = __builtin_amdgcn_mfma_f32_16x16x32_bf16(Bt[n][k], At[m][k], acc[ai][bj][m][n], 0, 0, 0); __builtin_amdgcn_s_setprio(0); } while (0)
; #define PG8_WAIT_V89() do { if constexpr (SLIVER) PG8_WAIT_V(9); else PG8_WAIT_V(8); } while (0)
; #define PG8_LDS_S(b) do { if constexpr (SLIVER) { Sf[0] = *(const PG8_LAS bf16x8*)(lds + STAGE_BYTES + (b) * 2048 + soff0); Sf[1] = *(const PG8_LAS bf16x8*)(lds + STAGE_BYTES + (b) * 2048 + (soff0 ^ 64)); } } while (0)
; #define PG8_WAIT_L(n) asm volatile("s_waitcnt lgkmcnt(" #n ")" ::: "memory")
; #define PG8_BAR __builtin_amdgcn_s_barrier()
; #define PG8_SCHED __builtin_amdgcn_sched_barrier(0)
; template <class Epi, class Sched, bool ALIGN_EPI = false, bool SP2 = false, bool SLIVER = false>
; __device__ __forceinline__ void gemm_phase(PG8_LAS unsigned char* lds, const Gemm g, const Sched& S, const Epi& E) {
;     ...
;             PG8_WAIT_V89(); PG8_WAIT_L(0); PG8_BAR; PG8_MMA(0, 0, At, B0); PG8_MMA(0, 1, At, B1); PG8_BAR; PG8_SCHED;
;             PG8_LDA(At, 0, 1); PG8_LDS_S(0); PG8_STAGE(PG8_SB(0, 0), b2, voffB); PG8_STAGE(PG8_SB(0, 1), b2 + hstep, voffB); PG8_STAGE(PG8_SA(0, 0), a2, voffA);
;             PG8_WAIT_V89(); PG8_WAIT_L(0); PG8_BAR; PG8_MMA(1, 0, At, B0); PG8_MMA(1, 1, At, B1); PG8_MMA_S(); PG8_BAR; PG8_SCHED;
	s_setprio 0
	s_add_i32 s83, 0, 0x20000
	v_lshl_add_u64 v[202:203], s[78:79], 0, v[190:191]
	s_add_i32 s78, s96, s18
	v_add_u32_e32 v178, s83, v213
	v_add_u32_e32 v184, s83, v214
	s_mov_b32 m0, s78
	ds_read_b128 v[138:141], v215 offset:16384
	ds_read_b128 v[142:145], v215 offset:17408
	ds_read_b128 v[216:219], v215 offset:18432
	ds_read_b128 v[220:223], v215 offset:19456
	ds_read_b128 v[224:227], v215 offset:20480
	ds_read_b128 v[228:231], v215 offset:21504
	ds_read_b128 v[232:235], v215 offset:22528
	ds_read_b128 v[240:243], v215 offset:23552
	ds_read_b128 v[180:183], v178
	ds_read_b128 v[184:187], v184
	global_load_lds_dwordx4 v[202:203], off
	v_lshl_add_u64 v[208:209], v[202:203], 0, s[20:21]
	s_add_i32 m0, s78, 0x2000
	s_add_i32 s77, s77, s18
	global_load_lds_dwordx4 v[208:209], off
	v_lshl_add_u64 v[208:209], v[202:203], 0, s[22:23]
	s_mov_b32 m0, s77
	v_lshl_add_u64 v[210:211], s[40:41], 0, v[188:189]
	global_load_lds_dwordx4 v[208:209], off
	v_lshl_add_u64 v[208:209], v[202:203], 0, s[24:25]
	s_add_i32 m0, s77, 0x2000
	s_nop 0
	global_load_lds_dwordx4 v[208:209], off
	s_mov_b32 m0, s85
	v_lshl_add_u64 v[208:209], v[210:211], 0, s[20:21]
	global_load_lds_dwordx4 v[210:211], off
	s_mov_b32 m0, s19
	s_nop 0
	global_load_lds_dwordx4 v[208:209], off
	s_waitcnt vmcnt(9)
	s_waitcnt lgkmcnt(0)
	s_setprio 1
	s_barrier
	v_mfma_f32_16x16x32_bf16 v[70:73], v[146:149], v[138:141], v[70:73]
	v_mfma_f32_16x16x32_bf16 v[66:69], v[154:157], v[138:141], v[66:69]
	v_mfma_f32_16x16x32_bf16 v[54:57], v[146:149], v[216:219], v[54:57]
	v_mfma_f32_16x16x32_bf16 v[50:53], v[154:157], v[216:219], v[50:53]
	v_mfma_f32_16x16x32_bf16 v[38:41], v[146:149], v[224:227], v[38:41]
	v_mfma_f32_16x16x32_bf16 v[34:37], v[154:157], v[224:227], v[34:37]
	v_mfma_f32_16x16x32_bf16 v[22:25], v[146:149], v[232:235], v[22:25]
	v_mfma_f32_16x16x32_bf16 v[18:21], v[154:157], v[232:235], v[18:21]
	v_mfma_f32_16x16x32_bf16 v[70:73], v[150:153], v[142:145], v[70:73]
	v_mfma_f32_16x16x32_bf16 v[66:69], v[158:161], v[142:145], v[66:69]
	v_mfma_f32_16x16x32_bf16 v[54:57], v[150:153], v[220:223], v[54:57]
	v_mfma_f32_16x16x32_bf16 v[50:53], v[158:161], v[220:223], v[50:53]
	v_mfma_f32_16x16x32_bf16 v[38:41], v[150:153], v[228:231], v[38:41]
	v_mfma_f32_16x16x32_bf16 v[34:37], v[158:161], v[228:231], v[34:37]
	v_mfma_f32_16x16x32_bf16 v[22:25], v[150:153], v[240:243], v[22:25]
	v_mfma_f32_16x16x32_bf16 v[18:21], v[158:161], v[240:243], v[18:21]
	v_mfma_f32_16x16x32_bf16 v[62:65], v[166:169], v[138:141], v[62:65]
	v_mfma_f32_16x16x32_bf16 v[58:61], v[174:177], v[138:141], v[58:61]
	v_mfma_f32_16x16x32_bf16 v[46:49], v[166:169], v[216:219], v[46:49]
	v_mfma_f32_16x16x32_bf16 v[42:45], v[174:177], v[216:219], v[42:45]
	v_mfma_f32_16x16x32_bf16 v[30:33], v[166:169], v[224:227], v[30:33]
	v_mfma_f32_16x16x32_bf16 v[26:29], v[174:177], v[224:227], v[26:29]
	v_mfma_f32_16x16x32_bf16 v[14:17], v[166:169], v[232:235], v[14:17]
	v_mfma_f32_16x16x32_bf16 v[10:13], v[174:177], v[232:235], v[10:13]
	v_mfma_f32_16x16x32_bf16 v[62:65], v[170:173], v[142:145], v[62:65]
	v_mfma_f32_16x16x32_bf16 v[58:61], v[162:165], v[142:145], v[58:61]
	v_mfma_f32_16x16x32_bf16 v[46:49], v[170:173], v[220:223], v[46:49]
	v_mfma_f32_16x16x32_bf16 v[42:45], v[162:165], v[220:223], v[42:45]
	v_mfma_f32_16x16x32_bf16 v[30:33], v[170:173], v[228:231], v[30:33]
	v_mfma_f32_16x16x32_bf16 v[26:29], v[162:165], v[228:231], v[26:29]
	v_mfma_f32_16x16x32_bf16 v[14:17], v[170:173], v[240:243], v[14:17]
	v_mfma_f32_16x16x32_bf16 v[10:13], v[162:165], v[240:243], v[10:13]
	s_setprio 0
	s_setprio 1
	v_cndmask_b32_e64 v138, 0, 1, s[52:53]
	v_cmp_ne_u32_e64 s[40:41], 1, v138
	s_andn2_b64 vcc, exec, s[52:53]
	s_mov_b64 s[96:97], -1
	s_cbranch_vccnz .LBB0_600
	v_mfma_f32_16x16x32_bf16 v[138:141], v[166:169], v[180:183], v[6:9]
	s_mov_b64 s[96:97], 0
	v_mfma_f32_16x16x32_bf16 v[142:145], v[174:177], v[180:183], v[2:5]
	v_mfma_f32_16x16x32_bf16 v[138:141], v[170:173], v[184:187], v[138:141]
	v_mfma_f32_16x16x32_bf16 v[142:145], v[162:165], v[184:187], v[142:145]

; #define PG8_SB(B) __builtin_amdgcn_rcpf(1.f + expneg(B))
; #define PG8_SB(B) __builtin_amdgcn_rcpf(1.f + expneg(B))
; #define PG8_STAGE(bufoff, gbase, voff) do { _Pragma("unroll") for (int _i = 0; _i < 2; ++_i) \
;         __builtin_amdgcn_global_load_lds((const unsigned*)((const char*)(gbase) + (size_t)_i * qstep + (voff)[0]), (PG8_LAS unsigned*)(lds + (bufoff) + ldsw + _i * 8192), 16, 0, 0); } while (0)
; #define PG8_LDA(dst, b, h) do { _Pragma("unroll") for (int m = 0; m < 4; ++m) _Pragma("unroll") for (int k = 0; k < 2; ++k) dst[m][k] = *(const PG8_LAS bf16x8*)(lds + PG8_SA(b, h) + aoff + m * 2048 + k * 1024); } while (0)
; #define PG8_LDB(dst, b, h) do { _Pragma("unroll") for (int n = 0; n < 2; ++n) _Pragma("unroll") for (int k = 0; k < 2; ++k) dst[n][k] = *(const PG8_LAS bf16x8*)(lds + PG8_SB(b, h) + boff + n * 2048 + k * 1024); } while (0)
; #define PG8_WAIT_L(n) asm volatile("s_waitcnt lgkmcnt(" #n ")" ::: "memory")
; template <class Epi, class Sched, bool ALIGN_EPI = false, bool SP2 = false, bool SLIVER = false>
; __device__ __forceinline__ void gemm_phase(PG8_LAS unsigned char* lds, const Gemm g, const Sched& S, const Epi& E) {
;     ...
;             const char* a2 = last ? nA : cA + (size_t)(t + 2) * kstep; const char* b2 = last ? nB : cB + (size_t)(t + 2) * kstep;
;             const char* a3 = a2 + kstep; const char* b3 = b2 + kstep;
;             const char* s1 = cS + (size_t)(t + 1) * kstep; const char* s2 = last ? nS : cS + (size_t)(t + 2) * kstep;
;             if (last && has_next) S.a_ready(nxt);
;             if constexpr (SP2) {
;             PG8_LDB(B0, 0, 0); PG8_LDB(B1, 0, 1); PG8_SCHED; PG8_LDA(At, 0, 0); PG8_STAGE(PG8_SA(1, 1), a1 + hstep, voffA); PG8_STAGE_S(1, s1);
;             PG8_WAIT_V89(); PG8_WAIT_L(0); PG8_BAR; PG8_MMA(0, 0, At, B0); PG8_MMA(0, 1, At, B1); PG8_BAR; PG8_SCHED;
;             PG8_LDA(At, 0, 1); PG8_LDS_S(0); PG8_STAGE(PG8_SB(0, 0), b2, voffB); PG8_STAGE(PG8_SB(0, 1), b2 + hstep, voffB); PG8_STAGE(PG8_SA(0, 0), a2, voffA);
;             PG8_WAIT_V89(); PG8_WAIT_L(0); PG8_BAR; PG8_MMA(1, 0, At, B0); PG8_MMA(1, 1, At, B1); PG8_MMA_S(); PG8_BAR; PG8_SCHED;
;             PG8_LDB(B0, 1, 0); PG8_LDB(B1, 1, 1); PG8_SCHED; PG8_LDA(At, 1, 0); PG8_STAGE(PG8_SA(0, 1), a2 + hstep, voffA); PG8_STAGE_S(0, s2);
;             PG8_WAIT_V89(); PG8_WAIT_L(0); PG8_BAR; PG8_MMA(0, 0, At, B0); PG8_MMA(0, 1, At, B1); PG8_BAR; PG8_SCHED;
.LBB0_602:
	s_add_u32 s77, s94, s62
	s_addc_u32 s78, s95, s63
	s_add_u32 s77, s77, 0x100
	s_addc_u32 s83, s78, 0
	s_and_b64 s[78:79], s[80:81], exec
	s_cselect_b32 s79, s66, s83
	s_cselect_b32 s78, s67, s77
	s_barrier
	s_setprio 0
	s_add_i32 s77, 0, 0x18000
	v_add_u32_e32 v2, s77, v212
	s_add_i32 s80, 0, 0x1c000
	ds_read_b128 v[146:149], v2
	ds_read_b128 v[150:153], v2 offset:1024
	ds_read_b128 v[154:157], v2 offset:2048
	ds_read_b128 v[158:161], v2 offset:3072
	v_add_u32_e32 v2, s80, v212
	ds_read_b128 v[166:169], v2
	ds_read_b128 v[170:173], v2 offset:1024
	ds_read_b128 v[174:177], v2 offset:2048
	ds_read_b128 v[162:165], v2 offset:3072
	s_mov_b32 m0, s49
	v_lshl_add_u64 v[208:209], v[210:211], 0, s[22:23]
	ds_read_b128 v[2:5], v215 offset:32768
	ds_read_b128 v[6:9], v215 offset:33792
	ds_read_b128 v[180:183], v215 offset:34816
	ds_read_b128 v[184:187], v215 offset:35840
	ds_read_b128 v[216:219], v215 offset:36864
	ds_read_b128 v[220:223], v215 offset:37888
	ds_read_b128 v[224:227], v215 offset:38912
	ds_read_b128 v[228:231], v215 offset:39936
	global_load_lds_dwordx4 v[208:209], off
	v_lshl_add_u64 v[208:209], v[210:211], 0, s[24:25]
	s_mov_b32 m0, s50
	s_nop 0
	global_load_lds_dwordx4 v[208:209], off
	v_lshl_add_u64 v[208:209], s[78:79], 0, v[192:193]
	s_mov_b32 m0, s51
	s_nop 0
	global_load_lds_dword v[208:209], off
	s_waitcnt vmcnt(9)
	s_waitcnt lgkmcnt(0)
	s_setprio 1
	s_barrier
	v_mfma_f32_16x16x32_bf16 v[134:137], v[146:149], v[2:5], v[134:137]
	v_mfma_f32_16x16x32_bf16 v[130:133], v[154:157], v[2:5], v[130:133]
	v_mfma_f32_16x16x32_bf16 v[118:121], v[146:149], v[180:183], v[118:121]
	v_mfma_f32_16x16x32_bf16 v[114:117], v[154:157], v[180:183], v[114:117]
	v_mfma_f32_16x16x32_bf16 v[102:105], v[146:149], v[216:219], v[102:105]
	v_mfma_f32_16x16x32_bf16 v[98:101], v[154:157], v[216:219], v[98:101]
	v_mfma_f32_16x16x32_bf16 v[86:89], v[146:149], v[224:227], v[86:89]
	v_mfma_f32_16x16x32_bf16 v[82:85], v[154:157], v[224:227], v[82:85]
	v_mfma_f32_16x16x32_bf16 v[134:137], v[150:153], v[6:9], v[134:137]
	v_mfma_f32_16x16x32_bf16 v[130:133], v[158:161], v[6:9], v[130:133]
	v_mfma_f32_16x16x32_bf16 v[118:121], v[150:153], v[184:187], v[118:121]
	v_mfma_f32_16x16x32_bf16 v[114:117], v[158:161], v[184:187], v[114:117]
	v_mfma_f32_16x16x32_bf16 v[102:105], v[150:153], v[220:223], v[102:105]
	v_mfma_f32_16x16x32_bf16 v[98:101], v[158:161], v[220:223], v[98:101]
	v_mfma_f32_16x16x32_bf16 v[86:89], v[150:153], v[228:231], v[86:89]
	v_mfma_f32_16x16x32_bf16 v[82:85], v[158:161], v[228:231], v[82:85]
	v_mfma_f32_16x16x32_bf16 v[126:129], v[166:169], v[2:5], v[126:129]
	v_mfma_f32_16x16x32_bf16 v[2:5], v[174:177], v[2:5], v[122:125]
	v_mfma_f32_16x16x32_bf16 v[122:125], v[162:165], v[6:9], v[2:5]
	v_mfma_f32_16x16x32_bf16 v[2:5], v[166:169], v[180:183], v[110:113]
	v_mfma_f32_16x16x32_bf16 v[110:113], v[170:173], v[184:187], v[2:5]
	v_mfma_f32_16x16x32_bf16 v[2:5], v[174:177], v[180:183], v[106:109]
	v_mfma_f32_16x16x32_bf16 v[106:109], v[162:165], v[184:187], v[2:5]
	v_mfma_f32_16x16x32_bf16 v[2:5], v[166:169], v[216:219], v[94:97]
	v_mfma_f32_16x16x32_bf16 v[94:97], v[170:173], v[220:223], v[2:5]
	v_mfma_f32_16x16x32_bf16 v[2:5], v[174:177], v[216:219], v[90:93]
	v_mfma_f32_16x16x32_bf16 v[90:93], v[162:165], v[220:223], v[2:5]
	v_mfma_f32_16x16x32_bf16 v[2:5], v[166:169], v[224:227], v[78:81]
	v_mfma_f32_16x16x32_bf16 v[78:81], v[170:173], v[228:231], v[2:5]
	v_mfma_f32_16x16x32_bf16 v[2:5], v[174:177], v[224:227], v[74:77]
	v_mfma_f32_16x16x32_bf16 v[126:129], v[170:173], v[6:9], v[126:129]
	v_mfma_f32_16x16x32_bf16 v[74:77], v[162:165], v[228:231], v[2:5]
	s_barrier
; #define PG8_SB(B) __builtin_amdgcn_rcpf(1.f + expneg(B))
; #define PG8_SB(B) __builtin_amdgcn_rcpf(1.f + expneg(B))
; #define PG8_STAGE(bufoff, gbase, voff) do { _Pragma("unroll") for (int _i = 0; _i < 2; ++_i) \
;         __builtin_amdgcn_global_load_lds((const unsigned*)((const char*)(gbase) + (size_t)_i * qstep + (voff)[0]), (PG8_LAS unsigned*)(lds + (bufoff) + ldsw + _i * 8192), 16, 0, 0); } while (0)
; #define PG8_LDA(dst, b, h) do { _Pragma("unroll") for (int m = 0; m < 4; ++m) _Pragma("unroll") for (int k = 0; k < 2; ++k) dst[m][k] = *(const PG8_LAS bf16x8*)(lds + PG8_SA(b, h) + aoff + m * 2048 + k * 1024); } while (0)
; #define PG8_MMA(ai, bj, At, Bt) do { __builtin_amdgcn_s_setprio(1); _Pragma("unroll") for (int m = 0; m < 4; ++m) _Pragma("unroll") for (int n = 0; n < 2; ++n) _Pragma("unroll") for (int k = 0; k < 2; ++k) \
;         acc[ai][bj][m][n] = __builtin_amdgcn_mfma_f32_16x16x32_bf16(Bt[n][k], At[m][k], acc[ai][bj][m][n], 0, 0, 0); __builtin_amdgcn_s_setprio(0); } while (0)
; #define PG8_WAIT_V89() do { if constexpr (SLIVER) PG8_WAIT_V(9); else PG8_WAIT_V(8); } while (0)
; #define PG8_LDS_S(b) do { if constexpr (SLIVER) { Sf[0] = *(const PG8_LAS bf16x8*)(lds + STAGE_BYTES + (b) * 2048 + soff0); Sf[1] = *(const PG8_LAS bf16x8*)(lds + STAGE_BYTES + (b) * 2048 + (soff0 ^ 64)); } } while (0)
; #define PG8_WAIT_L(n) asm volatile("s_waitcnt lgkmcnt(" #n ")" ::: "memory")
; #define PG8_BAR __builtin_amdgcn_s_barrier()
; #define PG8_SCHED __builtin_amdgcn_sched_barrier(0)
; template <class Epi, class Sched, bool ALIGN_EPI = false, bool SP2 = false, bool SLIVER = false>
; __device__ __forceinline__ void gemm_phase(PG8_LAS unsigned char* lds, const Gemm g, const Sched& S, const Epi& E) {
;     ...
;             PG8_LDA(At, 1, 1); PG8_LDS_S(1); PG8_STAGE(PG8_SB(1, 0), b3, voffB); PG8_STAGE(PG8_SB(1, 1), b3 + hstep, voffB); PG8_STAGE(PG8_SA(1, 0), a3, voffA);
;             PG8_WAIT_V89(); PG8_WAIT_L(0); PG8_BAR; PG8_MMA(1, 0, At, B0); PG8_MMA(1, 1, At, B1); PG8_MMA_S(); PG8_BAR; PG8_SCHED;
	s_setprio 0
	s_add_i32 s78, 0, 0x20800
	s_add_i32 s77, s77, s18
	v_add_u32_e32 v178, s78, v213
	v_add_u32_e32 v184, s78, v214
	v_lshl_add_u64 v[208:209], v[202:203], 0, s[26:27]
	s_mov_b32 m0, s77
	ds_read_b128 v[2:5], v215 offset:49152
	ds_read_b128 v[6:9], v215 offset:50176
	ds_read_b128 v[216:219], v215 offset:51200
	ds_read_b128 v[220:223], v215 offset:52224
	ds_read_b128 v[224:227], v215 offset:53248
	ds_read_b128 v[228:231], v215 offset:54272
	ds_read_b128 v[232:235], v215 offset:55296
	ds_read_b128 v[240:243], v215 offset:56320
	ds_read_b128 v[180:183], v178
	ds_read_b128 v[184:187], v184
	global_load_lds_dwordx4 v[208:209], off
	v_lshl_add_u64 v[208:209], v[202:203], 0, s[28:29]
	s_add_i32 m0, s77, 0x2000
	s_add_i32 s77, s80, s18
	global_load_lds_dwordx4 v[208:209], off
	v_lshl_add_u64 v[208:209], v[202:203], 0, s[30:31]
	s_mov_b32 m0, s77
	v_lshl_add_u64 v[202:203], v[202:203], 0, s[34:35]
	global_load_lds_dwordx4 v[208:209], off
	s_add_i32 m0, s77, 0x2000
	s_nop 0
	global_load_lds_dwordx4 v[202:203], off
	v_lshl_add_u64 v[202:203], v[210:211], 0, s[26:27]
	s_mov_b32 m0, s10
	s_nop 0
	global_load_lds_dwordx4 v[202:203], off
	v_lshl_add_u64 v[202:203], v[210:211], 0, s[28:29]
	s_mov_b32 m0, s2
	s_nop 0
	global_load_lds_dwordx4 v[202:203], off
	s_waitcnt vmcnt(9)
	s_waitcnt lgkmcnt(0)
	s_setprio 1
	s_barrier
	v_mfma_f32_16x16x32_bf16 v[70:73], v[146:149], v[2:5], v[70:73]
	v_mfma_f32_16x16x32_bf16 v[66:69], v[154:157], v[2:5], v[66:69]
	v_mfma_f32_16x16x32_bf16 v[54:57], v[146:149], v[216:219], v[54:57]
	v_mfma_f32_16x16x32_bf16 v[50:53], v[154:157], v[216:219], v[50:53]
	v_mfma_f32_16x16x32_bf16 v[38:41], v[146:149], v[224:227], v[38:41]
	v_mfma_f32_16x16x32_bf16 v[34:37], v[154:157], v[224:227], v[34:37]
	v_mfma_f32_16x16x32_bf16 v[22:25], v[146:149], v[232:235], v[22:25]
	v_mfma_f32_16x16x32_bf16 v[18:21], v[154:157], v[232:235], v[18:21]
	v_mfma_f32_16x16x32_bf16 v[70:73], v[150:153], v[6:9], v[70:73]
	v_mfma_f32_16x16x32_bf16 v[66:69], v[158:161], v[6:9], v[66:69]
	v_mfma_f32_16x16x32_bf16 v[54:57], v[150:153], v[220:223], v[54:57]
	v_mfma_f32_16x16x32_bf16 v[50:53], v[158:161], v[220:223], v[50:53]
	v_mfma_f32_16x16x32_bf16 v[38:41], v[150:153], v[228:231], v[38:41]
	v_mfma_f32_16x16x32_bf16 v[34:37], v[158:161], v[228:231], v[34:37]
	v_mfma_f32_16x16x32_bf16 v[22:25], v[150:153], v[240:243], v[22:25]
	v_mfma_f32_16x16x32_bf16 v[18:21], v[158:161], v[240:243], v[18:21]
	v_mfma_f32_16x16x32_bf16 v[62:65], v[166:169], v[2:5], v[62:65]
	v_mfma_f32_16x16x32_bf16 v[2:5], v[174:177], v[2:5], v[58:61]
	v_mfma_f32_16x16x32_bf16 v[58:61], v[162:165], v[6:9], v[2:5]
	v_mfma_f32_16x16x32_bf16 v[2:5], v[166:169], v[216:219], v[46:49]
	v_mfma_f32_16x16x32_bf16 v[46:49], v[170:173], v[220:223], v[2:5]
	v_mfma_f32_16x16x32_bf16 v[2:5], v[174:177], v[216:219], v[42:45]
	v_mfma_f32_16x16x32_bf16 v[42:45], v[162:165], v[220:223], v[2:5]
	v_mfma_f32_16x16x32_bf16 v[2:5], v[166:169], v[224:227], v[30:33]
	v_mfma_f32_16x16x32_bf16 v[30:33], v[170:173], v[228:231], v[2:5]
	v_mfma_f32_16x16x32_bf16 v[2:5], v[174:177], v[224:227], v[26:29]
	v_mfma_f32_16x16x32_bf16 v[26:29], v[162:165], v[228:231], v[2:5]
	v_mfma_f32_16x16x32_bf16 v[2:5], v[166:169], v[232:235], v[14:17]
	v_mfma_f32_16x16x32_bf16 v[14:17], v[170:173], v[240:243], v[2:5]
	v_mfma_f32_16x16x32_bf16 v[2:5], v[174:177], v[232:235], v[10:13]
	v_mfma_f32_16x16x32_bf16 v[62:65], v[170:173], v[6:9], v[62:65]
	v_mfma_f32_16x16x32_bf16 v[10:13], v[162:165], v[240:243], v[2:5]
	s_setprio 0
	s_setprio 1
	s_and_b64 vcc, exec, s[40:41]
	s_mov_b64 s[40:41], -1
	s_cbranch_vccnz .LBB0_604
	v_mfma_f32_16x16x32_bf16 v[2:5], v[166:169], v[180:183], v[138:141]
	s_mov_b64 s[40:41], 0
	v_mfma_f32_16x16x32_bf16 v[6:9], v[170:173], v[184:187], v[2:5]
	v_mfma_f32_16x16x32_bf16 v[2:5], v[174:177], v[180:183], v[142:145]
	v_mfma_f32_16x16x32_bf16 v[2:5], v[162:165], v[184:187], v[2:5]

; #define PG8_SB(B) __builtin_amdgcn_rcpf(1.f + expneg(B))
; #define PG8_SB(B) __builtin_amdgcn_rcpf(1.f + expneg(B))
; #define PG8_STAGE(bufoff, gbase, voff) do { _Pragma("unroll") for (int _i = 0; _i < 2; ++_i) \
;         __builtin_amdgcn_global_load_lds((const unsigned*)((const char*)(gbase) + (size_t)_i * qstep + (voff)[0]), (PG8_LAS unsigned*)(lds + (bufoff) + ldsw + _i * 8192), 16, 0, 0); } while (0)
; #define PG8_LDA(dst, b, h) do { _Pragma("unroll") for (int m = 0; m < 4; ++m) _Pragma("unroll") for (int k = 0; k < 2; ++k) dst[m][k] = *(const PG8_LAS bf16x8*)(lds + PG8_SA(b, h) + aoff + m * 2048 + k * 1024); } while (0)
; #define PG8_MMA(ai, bj, At, Bt) do { __builtin_amdgcn_s_setprio(1); _Pragma("unroll") for (int m = 0; m < 4; ++m) _Pragma("unroll") for (int n = 0; n < 2; ++n) _Pragma("unroll") for (int k = 0; k < 2; ++k) \
;         acc[ai][bj][m][n] = __builtin_amdgcn_mfma_f32_16x16x32_bf16(Bt[n][k], At[m][k], acc[ai][bj][m][n], 0, 0, 0); __builtin_amdgcn_s_setprio(0); } while (0)
; #define PG8_WAIT_V89() do { if constexpr (SLIVER) PG8_WAIT_V(9); else PG8_WAIT_V(8); } while (0)
; #define PG8_LDS_S(b) do { if constexpr (SLIVER) { Sf[0] = *(const PG8_LAS bf16x8*)(lds + STAGE_BYTES + (b) * 2048 + soff0); Sf[1] = *(const PG8_LAS bf16x8*)(lds + STAGE_BYTES + (b) * 2048 + (soff0 ^ 64)); } } while (0)
; #define PG8_WAIT_L(n) asm volatile("s_waitcnt lgkmcnt(" #n ")" ::: "memory")
; #define PG8_BAR __builtin_amdgcn_s_barrier()
; #define PG8_SCHED __builtin_amdgcn_sched_barrier(0)
; template <class Epi, class Sched, bool ALIGN_EPI = false, bool SP2 = false, bool SLIVER = false>
; __device__ __forceinline__ void gemm_phase(PG8_LAS unsigned char* lds, const Gemm g, const Sched& S, const Epi& E) {
;     ...
;             PG8_WAIT_V89(); PG8_WAIT_L(0); PG8_BAR; PG8_MMA(0, 0, At, B0); PG8_MMA(0, 1, At, B1); PG8_BAR; PG8_SCHED;
;             PG8_LDA(At, 0, 1); PG8_LDS_S(0); PG8_STAGE(PG8_SB(0, 0), b2, voffB); PG8_STAGE(PG8_SB(0, 1), b2 + hstep, voffB); PG8_STAGE(PG8_SA(0, 0), a2, voffA);
;             PG8_WAIT_V89(); PG8_WAIT_L(0); PG8_BAR; PG8_MMA(1, 0, At, B0); PG8_MMA(1, 1, At, B1); PG8_MMA_S(); PG8_BAR; PG8_SCHED;
.Lgup_skipw0:
	s_waitcnt lgkmcnt(0)
	s_setprio 1
	s_barrier
	v_mfma_f32_16x16x32_bf16 v[126:129], v[130:133], v[172:175], v[126:129]
	v_mfma_f32_16x16x32_bf16 v[118:121], v[148:151], v[172:175], v[118:121]
	v_mfma_f32_16x16x32_bf16 v[110:113], v[130:133], v[184:187], v[110:113]
	v_mfma_f32_16x16x32_bf16 v[102:105], v[148:151], v[184:187], v[102:105]
	v_mfma_f32_16x16x32_bf16 v[94:97], v[130:133], v[192:195], v[94:97]
	v_mfma_f32_16x16x32_bf16 v[86:89], v[148:151], v[192:195], v[86:89]
	v_mfma_f32_16x16x32_bf16 v[78:81], v[130:133], v[200:203], v[78:81]
	v_mfma_f32_16x16x32_bf16 v[70:73], v[148:151], v[200:203], v[70:73]
	v_mfma_f32_16x16x32_bf16 v[126:129], v[138:141], v[180:183], v[126:129]
	v_mfma_f32_16x16x32_bf16 v[118:121], v[152:155], v[180:183], v[118:121]
	v_mfma_f32_16x16x32_bf16 v[110:113], v[138:141], v[188:191], v[110:113]
	v_mfma_f32_16x16x32_bf16 v[102:105], v[152:155], v[188:191], v[102:105]
	v_mfma_f32_16x16x32_bf16 v[94:97], v[138:141], v[196:199], v[94:97]
	v_mfma_f32_16x16x32_bf16 v[86:89], v[152:155], v[196:199], v[86:89]
	v_mfma_f32_16x16x32_bf16 v[78:81], v[138:141], v[210:213], v[78:81]
	v_mfma_f32_16x16x32_bf16 v[70:73], v[152:155], v[210:213], v[70:73]
	v_mfma_f32_16x16x32_bf16 v[122:125], v[156:159], v[172:175], v[122:125]
	v_mfma_f32_16x16x32_bf16 v[114:117], v[164:167], v[172:175], v[114:117]
	v_mfma_f32_16x16x32_bf16 v[106:109], v[156:159], v[184:187], v[106:109]
	v_mfma_f32_16x16x32_bf16 v[98:101], v[164:167], v[184:187], v[98:101]
	v_mfma_f32_16x16x32_bf16 v[90:93], v[156:159], v[192:195], v[90:93]
	v_mfma_f32_16x16x32_bf16 v[82:85], v[164:167], v[192:195], v[82:85]
	v_mfma_f32_16x16x32_bf16 v[74:77], v[156:159], v[200:203], v[74:77]
	v_mfma_f32_16x16x32_bf16 v[66:69], v[164:167], v[200:203], v[66:69]
	v_mfma_f32_16x16x32_bf16 v[122:125], v[160:163], v[180:183], v[122:125]
	v_mfma_f32_16x16x32_bf16 v[114:117], v[168:171], v[180:183], v[114:117]
	v_mfma_f32_16x16x32_bf16 v[106:109], v[160:163], v[188:191], v[106:109]
	v_mfma_f32_16x16x32_bf16 v[98:101], v[168:171], v[188:191], v[98:101]
	v_mfma_f32_16x16x32_bf16 v[90:93], v[160:163], v[196:199], v[90:93]
	v_mfma_f32_16x16x32_bf16 v[82:85], v[168:171], v[196:199], v[82:85]
	v_mfma_f32_16x16x32_bf16 v[74:77], v[160:163], v[210:213], v[74:77]
	v_mfma_f32_16x16x32_bf16 v[66:69], v[168:171], v[210:213], v[66:69]
	s_barrier
	s_setprio 0
	v_lshl_add_u64 v[144:145], s[76:77], 0, v[178:179]
	s_add_i32 s76, s78, s88
	s_mov_b32 m0, s76
	ds_read_b128 v[172:175], v147 offset:16384
	ds_read_b128 v[180:183], v147 offset:17408
	ds_read_b128 v[184:187], v147 offset:18432
	ds_read_b128 v[188:191], v147 offset:19456
	ds_read_b128 v[192:195], v147 offset:20480
	ds_read_b128 v[196:199], v147 offset:21504
	ds_read_b128 v[200:203], v147 offset:22528
	ds_read_b128 v[210:213], v147 offset:23552
	global_load_lds_dwordx4 v[144:145], off
	v_lshl_add_u64 v[176:177], v[144:145], 0, s[20:21]
	s_add_i32 m0, s76, 0x2000
	s_add_i32 s76, s79, s88
	global_load_lds_dwordx4 v[176:177], off
	v_lshl_add_u64 v[176:177], v[144:145], 0, s[22:23]
	s_mov_b32 m0, s76
	s_nop 0
	global_load_lds_dwordx4 v[176:177], off
	v_lshl_add_u64 v[176:177], v[144:145], 0, s[24:25]
	s_add_i32 m0, s76, 0x2000
	s_nop 0
	global_load_lds_dwordx4 v[176:177], off
	v_lshl_add_u64 v[176:177], s[80:81], 0, v[134:135]
	s_mov_b32 m0, s45
	v_lshl_add_u64 v[208:209], v[176:177], 0, s[20:21]
	global_load_lds_dwordx4 v[176:177], off
	s_mov_b32 m0, s83
	s_nop 0
	global_load_lds_dwordx4 v[208:209], off
	s_cmp_eq_u32 s69, s101
	s_cbranch_scc1 .Lgup_skipw1
	s_waitcnt vmcnt(8)
.Lgup_skipw1:
	s_waitcnt lgkmcnt(0)
	s_setprio 1
	s_barrier
	v_mfma_f32_16x16x32_bf16 v[62:65], v[130:133], v[172:175], v[62:65]
	v_mfma_f32_16x16x32_bf16 v[54:57], v[148:151], v[172:175], v[54:57]
	v_mfma_f32_16x16x32_bf16 v[46:49], v[130:133], v[184:187], v[46:49]
	v_mfma_f32_16x16x32_bf16 v[38:41], v[148:151], v[184:187], v[38:41]
	v_mfma_f32_16x16x32_bf16 v[30:33], v[130:133], v[192:195], v[30:33]
	v_mfma_f32_16x16x32_bf16 v[22:25], v[148:151], v[192:195], v[22:25]
	v_mfma_f32_16x16x32_bf16 v[14:17], v[130:133], v[200:203], v[14:17]
	v_mfma_f32_16x16x32_bf16 v[6:9], v[148:151], v[200:203], v[6:9]
	v_mfma_f32_16x16x32_bf16 v[62:65], v[138:141], v[180:183], v[62:65]
	v_mfma_f32_16x16x32_bf16 v[54:57], v[152:155], v[180:183], v[54:57]
	v_mfma_f32_16x16x32_bf16 v[46:49], v[138:141], v[188:191], v[46:49]
	v_mfma_f32_16x16x32_bf16 v[38:41], v[152:155], v[188:191], v[38:41]
	v_mfma_f32_16x16x32_bf16 v[30:33], v[138:141], v[196:199], v[30:33]
	v_mfma_f32_16x16x32_bf16 v[22:25], v[152:155], v[196:199], v[22:25]
	v_mfma_f32_16x16x32_bf16 v[14:17], v[138:141], v[210:213], v[14:17]
	v_mfma_f32_16x16x32_bf16 v[6:9], v[152:155], v[210:213], v[6:9]
	v_mfma_f32_16x16x32_bf16 v[58:61], v[156:159], v[172:175], v[58:61]
	v_mfma_f32_16x16x32_bf16 v[50:53], v[164:167], v[172:175], v[50:53]
	v_mfma_f32_16x16x32_bf16 v[42:45], v[156:159], v[184:187], v[42:45]
	v_mfma_f32_16x16x32_bf16 v[34:37], v[164:167], v[184:187], v[34:37]
	v_mfma_f32_16x16x32_bf16 v[26:29], v[156:159], v[192:195], v[26:29]
	v_mfma_f32_16x16x32_bf16 v[18:21], v[164:167], v[192:195], v[18:21]
	v_mfma_f32_16x16x32_bf16 v[10:13], v[156:159], v[200:203], v[10:13]
	v_mfma_f32_16x16x32_bf16 v[2:5], v[164:167], v[200:203], v[2:5]
	v_mfma_f32_16x16x32_bf16 v[58:61], v[160:163], v[180:183], v[58:61]
	v_mfma_f32_16x16x32_bf16 v[50:53], v[168:171], v[180:183], v[50:53]
	v_mfma_f32_16x16x32_bf16 v[42:45], v[160:163], v[188:191], v[42:45]
	v_mfma_f32_16x16x32_bf16 v[34:37], v[168:171], v[188:191], v[34:37]
	v_mfma_f32_16x16x32_bf16 v[26:29], v[160:163], v[196:199], v[26:29]
	v_mfma_f32_16x16x32_bf16 v[18:21], v[168:171], v[196:199], v[18:21]
	v_mfma_f32_16x16x32_bf16 v[10:13], v[160:163], v[210:213], v[10:13]
	v_mfma_f32_16x16x32_bf16 v[2:5], v[168:171], v[210:213], v[2:5]
	s_barrier
; #define PG8_SB(B) __builtin_amdgcn_rcpf(1.f + expneg(B))
; #define PG8_SB(B) __builtin_amdgcn_rcpf(1.f + expneg(B))
; #define PG8_STAGE(bufoff, gbase, voff) do { _Pragma("unroll") for (int _i = 0; _i < 2; ++_i) \
;         __builtin_amdgcn_global_load_lds((const unsigned*)((const char*)(gbase) + (size_t)_i * qstep + (voff)[0]), (PG8_LAS unsigned*)(lds + (bufoff) + ldsw + _i * 8192), 16, 0, 0); } while (0)
; #define PG8_LDA(dst, b, h) do { _Pragma("unroll") for (int m = 0; m < 4; ++m) _Pragma("unroll") for (int k = 0; k < 2; ++k) dst[m][k] = *(const PG8_LAS bf16x8*)(lds + PG8_SA(b, h) + aoff + m * 2048 + k * 1024); } while (0)
; #define PG8_LDB(dst, b, h) do { _Pragma("unroll") for (int n = 0; n < 2; ++n) _Pragma("unroll") for (int k = 0; k < 2; ++k) dst[n][k] = *(const PG8_LAS bf16x8*)(lds + PG8_SB(b, h) + boff + n * 2048 + k * 1024); } while (0)
; #define PG8_MMA(ai, bj, At, Bt) do { __builtin_amdgcn_s_setprio(1); _Pragma("unroll") for (int m = 0; m < 4; ++m) _Pragma("unroll") for (int n = 0; n < 2; ++n) _Pragma("unroll") for (int k = 0; k < 2; ++k) \
;         acc[ai][bj][m][n] = __builtin_amdgcn_mfma_f32_16x16x32_bf16(Bt[n][k], At[m][k], acc[ai][bj][m][n], 0, 0, 0); __builtin_amdgcn_s_setprio(0); } while (0)
; #define PG8_WAIT_V89() do { if constexpr (SLIVER) PG8_WAIT_V(9); else PG8_WAIT_V(8); } while (0)
; #define PG8_LDS_S(b) do { if constexpr (SLIVER) { Sf[0] = *(const PG8_LAS bf16x8*)(lds + STAGE_BYTES + (b) * 2048 + soff0); Sf[1] = *(const PG8_LAS bf16x8*)(lds + STAGE_BYTES + (b) * 2048 + (soff0 ^ 64)); } } while (0)
; template <class Epi, class Sched, bool ALIGN_EPI = false, bool SP2 = false, bool SLIVER = false>
; __device__ __forceinline__ void gemm_phase(PG8_LAS unsigned char* lds, const Gemm g, const Sched& S, const Epi& E) {
;     ...
;             PG8_LDB(B0, 1, 0); PG8_LDB(B1, 1, 1); PG8_SCHED; PG8_LDA(At, 1, 0); PG8_STAGE(PG8_SA(0, 1), a2 + hstep, voffA); PG8_STAGE_S(0, s2);
;             PG8_WAIT_V89(); PG8_WAIT_L(0); PG8_BAR; PG8_MMA(0, 0, At, B0); PG8_MMA(0, 1, At, B1); PG8_BAR; PG8_SCHED;
;             PG8_LDA(At, 1, 1); PG8_LDS_S(1); PG8_STAGE(PG8_SB(1, 0), b3, voffB); PG8_STAGE(PG8_SB(1, 1), b3 + hstep, voffB); PG8_STAGE(PG8_SA(1, 0), a3, voffA);
;             PG8_WAIT_V89(); PG8_WAIT_L(0); PG8_BAR; PG8_MMA(1, 0, At, B0); PG8_MMA(1, 1, At, B1); PG8_MMA_S(); PG8_BAR; PG8_SCHED;
;     ...
;         if constexpr (ALIGN_EPI) { if (wr == 0) PG8_BAR; }
	s_setprio 0
	s_add_i32 s76, 0, 0x18000
	v_add_u32_e32 v142, s76, v143
	s_add_i32 s77, 0, 0x1c000
	ds_read_b128 v[130:133], v142
	ds_read_b128 v[138:141], v142 offset:1024
	ds_read_b128 v[148:151], v142 offset:2048
	ds_read_b128 v[152:155], v142 offset:3072
	v_add_u32_e32 v142, s77, v143
	ds_read_b128 v[156:159], v142
	ds_read_b128 v[160:163], v142 offset:1024
	ds_read_b128 v[164:167], v142 offset:2048
	ds_read_b128 v[168:171], v142 offset:3072
	s_mov_b32 m0, s90
	v_lshl_add_u64 v[208:209], v[176:177], 0, s[22:23]
	ds_read_b128 v[172:175], v147 offset:32768
	ds_read_b128 v[180:183], v147 offset:33792
	ds_read_b128 v[184:187], v147 offset:34816
	ds_read_b128 v[188:191], v147 offset:35840
	ds_read_b128 v[192:195], v147 offset:36864
	ds_read_b128 v[196:199], v147 offset:37888
	ds_read_b128 v[200:203], v147 offset:38912
	ds_read_b128 v[210:213], v147 offset:39936
	global_load_lds_dwordx4 v[208:209], off
	v_lshl_add_u64 v[208:209], v[176:177], 0, s[24:25]
	s_mov_b32 m0, s91
	s_nop 0
	global_load_lds_dwordx4 v[208:209], off
	s_waitcnt vmcnt(8)
	s_waitcnt lgkmcnt(0)
	s_setprio 1
	s_barrier
	v_mfma_f32_16x16x32_bf16 v[126:129], v[130:133], v[172:175], v[126:129]
	v_mfma_f32_16x16x32_bf16 v[118:121], v[148:151], v[172:175], v[118:121]
	v_mfma_f32_16x16x32_bf16 v[110:113], v[130:133], v[184:187], v[110:113]
	v_mfma_f32_16x16x32_bf16 v[102:105], v[148:151], v[184:187], v[102:105]
	v_mfma_f32_16x16x32_bf16 v[94:97], v[130:133], v[192:195], v[94:97]
	v_mfma_f32_16x16x32_bf16 v[86:89], v[148:151], v[192:195], v[86:89]
	v_mfma_f32_16x16x32_bf16 v[78:81], v[130:133], v[200:203], v[78:81]
	v_mfma_f32_16x16x32_bf16 v[70:73], v[148:151], v[200:203], v[70:73]
	v_mfma_f32_16x16x32_bf16 v[126:129], v[138:141], v[180:183], v[126:129]
	v_mfma_f32_16x16x32_bf16 v[118:121], v[152:155], v[180:183], v[118:121]
	v_mfma_f32_16x16x32_bf16 v[110:113], v[138:141], v[188:191], v[110:113]
	v_mfma_f32_16x16x32_bf16 v[102:105], v[152:155], v[188:191], v[102:105]
	v_mfma_f32_16x16x32_bf16 v[94:97], v[138:141], v[196:199], v[94:97]
	v_mfma_f32_16x16x32_bf16 v[86:89], v[152:155], v[196:199], v[86:89]
	v_mfma_f32_16x16x32_bf16 v[78:81], v[138:141], v[210:213], v[78:81]
	v_mfma_f32_16x16x32_bf16 v[70:73], v[152:155], v[210:213], v[70:73]
	v_mfma_f32_16x16x32_bf16 v[122:125], v[156:159], v[172:175], v[122:125]
	v_mfma_f32_16x16x32_bf16 v[114:117], v[164:167], v[172:175], v[114:117]
	v_mfma_f32_16x16x32_bf16 v[106:109], v[156:159], v[184:187], v[106:109]
	v_mfma_f32_16x16x32_bf16 v[98:101], v[164:167], v[184:187], v[98:101]
	v_mfma_f32_16x16x32_bf16 v[90:93], v[156:159], v[192:195], v[90:93]
	v_mfma_f32_16x16x32_bf16 v[82:85], v[164:167], v[192:195], v[82:85]
	v_mfma_f32_16x16x32_bf16 v[74:77], v[156:159], v[200:203], v[74:77]
	v_mfma_f32_16x16x32_bf16 v[66:69], v[164:167], v[200:203], v[66:69]
	v_mfma_f32_16x16x32_bf16 v[122:125], v[160:163], v[180:183], v[122:125]
	v_mfma_f32_16x16x32_bf16 v[114:117], v[168:171], v[180:183], v[114:117]
	v_mfma_f32_16x16x32_bf16 v[106:109], v[160:163], v[188:191], v[106:109]
	v_mfma_f32_16x16x32_bf16 v[98:101], v[168:171], v[188:191], v[98:101]
	v_mfma_f32_16x16x32_bf16 v[90:93], v[160:163], v[196:199], v[90:93]
	v_mfma_f32_16x16x32_bf16 v[82:85], v[168:171], v[196:199], v[82:85]
	v_mfma_f32_16x16x32_bf16 v[74:77], v[160:163], v[210:213], v[74:77]
	v_mfma_f32_16x16x32_bf16 v[66:69], v[168:171], v[210:213], v[66:69]
	s_barrier
	s_setprio 0
	s_add_i32 s76, s76, s88
	v_lshl_add_u64 v[208:209], v[144:145], 0, s[26:27]
	s_mov_b32 m0, s76
	ds_read_b128 v[172:175], v147 offset:49152
	ds_read_b128 v[180:183], v147 offset:50176
	ds_read_b128 v[184:187], v147 offset:51200
	ds_read_b128 v[188:191], v147 offset:52224
	ds_read_b128 v[192:195], v147 offset:53248
	ds_read_b128 v[196:199], v147 offset:54272
	ds_read_b128 v[200:203], v147 offset:55296
	ds_read_b128 v[210:213], v147 offset:56320
	global_load_lds_dwordx4 v[208:209], off
	v_lshl_add_u64 v[208:209], v[144:145], 0, s[28:29]
	s_add_i32 m0, s76, 0x2000
	s_add_i32 s76, s77, s88
	global_load_lds_dwordx4 v[208:209], off
	v_lshl_add_u64 v[208:209], v[144:145], 0, s[30:31]
	s_mov_b32 m0, s76
	v_lshl_add_u64 v[144:145], v[144:145], 0, s[34:35]
	global_load_lds_dwordx4 v[208:209], off
	s_add_i32 m0, s76, 0x2000
	s_nop 0
	global_load_lds_dwordx4 v[144:145], off
	v_lshl_add_u64 v[144:145], v[176:177], 0, s[26:27]
	s_mov_b32 m0, s93
	s_nop 0
	global_load_lds_dwordx4 v[144:145], off
	v_lshl_add_u64 v[144:145], v[176:177], 0, s[28:29]
	s_mov_b32 m0, s94
	s_nop 0
	global_load_lds_dwordx4 v[144:145], off
	s_waitcnt vmcnt(8)
	s_waitcnt lgkmcnt(0)
	s_setprio 1
	s_barrier
	v_mfma_f32_16x16x32_bf16 v[62:65], v[130:133], v[172:175], v[62:65]
	v_mfma_f32_16x16x32_bf16 v[54:57], v[148:151], v[172:175], v[54:57]
	v_mfma_f32_16x16x32_bf16 v[46:49], v[130:133], v[184:187], v[46:49]
	v_mfma_f32_16x16x32_bf16 v[38:41], v[148:151], v[184:187], v[38:41]
	v_mfma_f32_16x16x32_bf16 v[30:33], v[130:133], v[192:195], v[30:33]
	v_mfma_f32_16x16x32_bf16 v[22:25], v[148:151], v[192:195], v[22:25]
	v_mfma_f32_16x16x32_bf16 v[14:17], v[130:133], v[200:203], v[14:17]
	v_mfma_f32_16x16x32_bf16 v[6:9], v[148:151], v[200:203], v[6:9]
	v_mfma_f32_16x16x32_bf16 v[62:65], v[138:141], v[180:183], v[62:65]
	v_mfma_f32_16x16x32_bf16 v[54:57], v[152:155], v[180:183], v[54:57]
	v_mfma_f32_16x16x32_bf16 v[46:49], v[138:141], v[188:191], v[46:49]
	v_mfma_f32_16x16x32_bf16 v[38:41], v[152:155], v[188:191], v[38:41]
	v_mfma_f32_16x16x32_bf16 v[30:33], v[138:141], v[196:199], v[30:33]
	v_mfma_f32_16x16x32_bf16 v[22:25], v[152:155], v[196:199], v[22:25]
	v_mfma_f32_16x16x32_bf16 v[14:17], v[138:141], v[210:213], v[14:17]
	v_mfma_f32_16x16x32_bf16 v[6:9], v[152:155], v[210:213], v[6:9]
	v_mfma_f32_16x16x32_bf16 v[58:61], v[156:159], v[172:175], v[58:61]
	v_mfma_f32_16x16x32_bf16 v[50:53], v[164:167], v[172:175], v[50:53]
	v_mfma_f32_16x16x32_bf16 v[42:45], v[156:159], v[184:187], v[42:45]
	v_mfma_f32_16x16x32_bf16 v[34:37], v[164:167], v[184:187], v[34:37]
	v_mfma_f32_16x16x32_bf16 v[26:29], v[156:159], v[192:195], v[26:29]
	v_mfma_f32_16x16x32_bf16 v[18:21], v[164:167], v[192:195], v[18:21]
	v_mfma_f32_16x16x32_bf16 v[10:13], v[156:159], v[200:203], v[10:13]
	v_mfma_f32_16x16x32_bf16 v[2:5], v[164:167], v[200:203], v[2:5]
	v_mfma_f32_16x16x32_bf16 v[58:61], v[160:163], v[180:183], v[58:61]
	v_mfma_f32_16x16x32_bf16 v[50:53], v[168:171], v[180:183], v[50:53]
	v_mfma_f32_16x16x32_bf16 v[42:45], v[160:163], v[188:191], v[42:45]
	v_mfma_f32_16x16x32_bf16 v[34:37], v[168:171], v[188:191], v[34:37]
	v_mfma_f32_16x16x32_bf16 v[26:29], v[160:163], v[196:199], v[26:29]
	v_mfma_f32_16x16x32_bf16 v[18:21], v[168:171], v[196:199], v[18:21]
	v_mfma_f32_16x16x32_bf16 v[10:13], v[160:163], v[210:213], v[10:13]
	v_mfma_f32_16x16x32_bf16 v[2:5], v[168:171], v[210:213], v[2:5]
	s_barrier
	s_setprio 0
	s_add_i32 s69, s69, 2
	s_add_u32 s62, s62, 0x100
	s_addc_u32 s63, s63, 0
	s_add_u32 s67, s67, 0x100
	s_addc_u32 s68, s68, 0
	s_cmp_gt_u32 s69, 29
	s_cbranch_scc0 .LBB0_705
	s_and_b64 vcc, exec, s[42:43]
	s_cbranch_vccz .LBB0_708
	s_barrier

; #define PG8_STAGE(bufoff, gbase, voff) do { _Pragma("unroll") for (int _i = 0; _i < 2; ++_i) \
;         __builtin_amdgcn_global_load_lds((const unsigned*)((const char*)(gbase) + (size_t)_i * qstep + (voff)[0]), (PG8_LAS unsigned*)(lds + (bufoff) + ldsw + _i * 8192), 16, 0, 0); } while (0)
; #define PG8_LDA(dst, b, h) do { _Pragma("unroll") for (int m = 0; m < 4; ++m) _Pragma("unroll") for (int k = 0; k < 2; ++k) dst[m][k] = *(const PG8_LAS bf16x8*)(lds + PG8_SA(b, h) + aoff + m * 2048 + k * 1024); } while (0)
; #define PG8_LDB(dst, b, h) do { _Pragma("unroll") for (int n = 0; n < 2; ++n) _Pragma("unroll") for (int k = 0; k < 2; ++k) dst[n][k] = *(const PG8_LAS bf16x8*)(lds + PG8_SB(b, h) + boff + n * 2048 + k * 1024); } while (0)
; #define PG8_MMA(ai, bj, At, Bt) do { __builtin_amdgcn_s_setprio(1); _Pragma("unroll") for (int m = 0; m < 4; ++m) _Pragma("unroll") for (int n = 0; n < 2; ++n) _Pragma("unroll") for (int k = 0; k < 2; ++k) \
;         acc[ai][bj][m][n] = __builtin_amdgcn_mfma_f32_16x16x32_bf16(Bt[n][k], At[m][k], acc[ai][bj][m][n], 0, 0, 0); __builtin_amdgcn_s_setprio(0); } while (0)
; #define PG8_WAIT_V89() do { if constexpr (SLIVER) PG8_WAIT_V(9); else PG8_WAIT_V(8); } while (0)
; #define PG8_WAIT_L(n) asm volatile("s_waitcnt lgkmcnt(" #n ")" ::: "memory")
; #define PG8_BAR __builtin_amdgcn_s_barrier()
; #define PG8_SCHED __builtin_amdgcn_sched_barrier(0)
; template <class Epi, class Sched, bool ALIGN_EPI = false, bool SP2 = false, bool SLIVER = false>
; __device__ __forceinline__ void gemm_phase(PG8_LAS unsigned char* lds, const Gemm g, const Sched& S, const Epi& E) {
;     ...
;             const bool last = (t == nt - 2);
;             const char* a1 = cA + (size_t)(t + 1) * kstep;
;             const char* a2 = last ? nA : cA + (size_t)(t + 2) * kstep; const char* b2 = last ? nB : cB + (size_t)(t + 2) * kstep;
;             const char* a3 = a2 + kstep; const char* b3 = b2 + kstep;
;             const char* s1 = cS + (size_t)(t + 1) * kstep; const char* s2 = last ? nS : cS + (size_t)(t + 2) * kstep;
;             if (last && has_next) S.a_ready(nxt);
;             if constexpr (SP2) {
;             PG8_LDB(B0, 0, 0); PG8_LDB(B1, 0, 1); PG8_SCHED; PG8_LDA(At, 0, 0); PG8_STAGE(PG8_SA(1, 1), a1 + hstep, voffA); PG8_STAGE_S(1, s1);
;             PG8_WAIT_V89(); PG8_WAIT_L(0); PG8_BAR; PG8_MMA(0, 0, At, B0); PG8_MMA(0, 1, At, B1); PG8_BAR; PG8_SCHED;
.LBB0_811:
	s_add_u32 s13, s90, s62
	s_addc_u32 s40, s91, s63
	s_add_u32 s13, s13, 0x100
	s_addc_u32 s66, s40, 0
	s_add_u32 s68, s2, s62
	s_addc_u32 s67, s3, s63
	s_add_i32 s69, 0, 0x10000
	s_cmpk_eq_i32 s62, 0x2b00
	s_cselect_b64 s[80:81], -1, 0
	s_and_b64 s[40:41], s[80:81], exec
	s_cselect_b32 s41, s85, s66
	s_cselect_b32 s40, s84, s13
	v_add_u32_e32 v66, s69, v220
	s_cselect_b32 s67, s87, s67
	s_cselect_b32 s66, s86, s68
	s_add_i32 s13, 0, 0x14000
	ds_read_b128 v[154:157], v66
	ds_read_b128 v[158:161], v66 offset:1024
	ds_read_b128 v[162:165], v66 offset:2048
	ds_read_b128 v[174:177], v66 offset:3072
	v_add_u32_e32 v66, s13, v220
	ds_read_b128 v[184:187], v66
	ds_read_b128 v[188:191], v66 offset:1024
	ds_read_b128 v[192:195], v66 offset:2048
	ds_read_b128 v[180:183], v66 offset:3072
	v_lshl_add_u64 v[146:147], v[214:215], 0, s[62:63]
	v_lshl_add_u64 v[148:149], v[146:147], 0, s[8:9]
	s_add_i32 m0, s19, 0xc000
	s_mov_b64 s[94:95], 0x210080
	ds_read_b128 v[66:69], v223
	ds_read_b128 v[70:73], v223 offset:1024
	ds_read_b128 v[74:77], v223 offset:2048
	ds_read_b128 v[78:81], v223 offset:3072
	ds_read_b128 v[216:219], v223 offset:4096
	ds_read_b128 v[224:227], v223 offset:5120
	ds_read_b128 v[228:231], v223 offset:6144
	ds_read_b128 v[232:235], v223 offset:7168
	global_load_lds_dwordx4 v[148:149], off
	v_lshl_add_u64 v[146:147], v[146:147], 0, s[94:95]
	s_add_i32 m0, s19, 0xe000
	s_nop 0
	global_load_lds_dwordx4 v[146:147], off
	v_lshl_add_u64 v[146:147], v[212:213], 0, s[62:63]
	s_add_i32 m0, s96, 0x20800
	s_nop 0
	global_load_lds_dword v[146:147], off
	s_waitcnt vmcnt(9)
	s_waitcnt lgkmcnt(0)
	s_setprio 1
	s_barrier
	v_mfma_f32_16x16x32_bf16 v[146:149], v[154:157], v[66:69], v[170:173]
	v_mfma_f32_16x16x32_bf16 v[150:153], v[162:165], v[66:69], v[166:169]
	v_mfma_f32_16x16x32_bf16 v[134:137], v[154:157], v[74:77], v[134:137]
	v_mfma_f32_16x16x32_bf16 v[130:133], v[162:165], v[74:77], v[130:133]
	v_mfma_f32_16x16x32_bf16 v[118:121], v[154:157], v[216:219], v[118:121]
	v_mfma_f32_16x16x32_bf16 v[114:117], v[162:165], v[216:219], v[114:117]
	v_mfma_f32_16x16x32_bf16 v[102:105], v[154:157], v[228:231], v[102:105]
	v_mfma_f32_16x16x32_bf16 v[98:101], v[162:165], v[228:231], v[98:101]
	v_mfma_f32_16x16x32_bf16 v[146:149], v[158:161], v[70:73], v[146:149]
	v_mfma_f32_16x16x32_bf16 v[150:153], v[174:177], v[70:73], v[150:153]
	v_mfma_f32_16x16x32_bf16 v[134:137], v[158:161], v[78:81], v[134:137]
	v_mfma_f32_16x16x32_bf16 v[130:133], v[174:177], v[78:81], v[130:133]
	v_mfma_f32_16x16x32_bf16 v[118:121], v[158:161], v[224:227], v[118:121]
	v_mfma_f32_16x16x32_bf16 v[114:117], v[174:177], v[224:227], v[114:117]
	v_mfma_f32_16x16x32_bf16 v[102:105], v[158:161], v[232:235], v[102:105]
	v_mfma_f32_16x16x32_bf16 v[98:101], v[174:177], v[232:235], v[98:101]
	v_mfma_f32_16x16x32_bf16 v[142:145], v[184:187], v[66:69], v[142:145]
	v_mfma_f32_16x16x32_bf16 v[66:69], v[192:195], v[66:69], v[138:141]
	v_mfma_f32_16x16x32_bf16 v[138:141], v[180:183], v[70:73], v[66:69]
	v_mfma_f32_16x16x32_bf16 v[66:69], v[184:187], v[74:77], v[126:129]
	v_mfma_f32_16x16x32_bf16 v[126:129], v[188:191], v[78:81], v[66:69]
	v_mfma_f32_16x16x32_bf16 v[66:69], v[192:195], v[74:77], v[122:125]
	v_mfma_f32_16x16x32_bf16 v[122:125], v[180:183], v[78:81], v[66:69]
	v_mfma_f32_16x16x32_bf16 v[66:69], v[184:187], v[216:219], v[110:113]
	v_mfma_f32_16x16x32_bf16 v[110:113], v[188:191], v[224:227], v[66:69]
	v_mfma_f32_16x16x32_bf16 v[66:69], v[192:195], v[216:219], v[106:109]
	v_mfma_f32_16x16x32_bf16 v[106:109], v[180:183], v[224:227], v[66:69]
	v_mfma_f32_16x16x32_bf16 v[66:69], v[184:187], v[228:231], v[94:97]
	v_mfma_f32_16x16x32_bf16 v[94:97], v[188:191], v[232:235], v[66:69]
	v_mfma_f32_16x16x32_bf16 v[66:69], v[192:195], v[228:231], v[90:93]
	v_mfma_f32_16x16x32_bf16 v[142:145], v[188:191], v[70:73], v[142:145]
	v_mfma_f32_16x16x32_bf16 v[90:93], v[180:183], v[232:235], v[66:69]
	s_barrier
; #define PG8_SB(B) __builtin_amdgcn_rcpf(1.f + expneg(B))
; #define PG8_SB(B) __builtin_amdgcn_rcpf(1.f + expneg(B))
; #define PG8_STAGE(bufoff, gbase, voff) do { _Pragma("unroll") for (int _i = 0; _i < 2; ++_i) \
;         __builtin_amdgcn_global_load_lds((const unsigned*)((const char*)(gbase) + (size_t)_i * qstep + (voff)[0]), (PG8_LAS unsigned*)(lds + (bufoff) + ldsw + _i * 8192), 16, 0, 0); } while (0)
; #define PG8_LDA(dst, b, h) do { _Pragma("unroll") for (int m = 0; m < 4; ++m) _Pragma("unroll") for (int k = 0; k < 2; ++k) dst[m][k] = *(const PG8_LAS bf16x8*)(lds + PG8_SA(b, h) + aoff + m * 2048 + k * 1024); } while (0)
; #define PG8_MMA(ai, bj, At, Bt) do { __builtin_amdgcn_s_setprio(1); _Pragma("unroll") for (int m = 0; m < 4; ++m) _Pragma("unroll") for (int n = 0; n < 2; ++n) _Pragma("unroll") for (int k = 0; k < 2; ++k) \
;         acc[ai][bj][m][n] = __builtin_amdgcn_mfma_f32_16x16x32_bf16(Bt[n][k], At[m][k], acc[ai][bj][m][n], 0, 0, 0); __builtin_amdgcn_s_setprio(0); } while (0)
; #define PG8_WAIT_V89() do { if constexpr (SLIVER) PG8_WAIT_V(9); else PG8_WAIT_V(8); } while (0)
; #define PG8_LDS_S(b) do { if constexpr (SLIVER) { Sf[0] = *(const PG8_LAS bf16x8*)(lds + STAGE_BYTES + (b) * 2048 + soff0); Sf[1] = *(const PG8_LAS bf16x8*)(lds + STAGE_BYTES + (b) * 2048 + (soff0 ^ 64)); } } while (0)
; #define PG8_WAIT_L(n) asm volatile("s_waitcnt lgkmcnt(" #n ")" ::: "memory")
; #define PG8_BAR __builtin_amdgcn_s_barrier()
; #define PG8_SCHED __builtin_amdgcn_sched_barrier(0)
; template <class Epi, class Sched, bool ALIGN_EPI = false, bool SP2 = false, bool SLIVER = false>
; __device__ __forceinline__ void gemm_phase(PG8_LAS unsigned char* lds, const Gemm g, const Sched& S, const Epi& E) {
;     ...
;             PG8_LDA(At, 0, 1); PG8_LDS_S(0); PG8_STAGE(PG8_SB(0, 0), b2, voffB); PG8_STAGE(PG8_SB(0, 1), b2 + hstep, voffB); PG8_STAGE(PG8_SA(0, 0), a2, voffA);
;             PG8_WAIT_V89(); PG8_WAIT_L(0); PG8_BAR; PG8_MMA(1, 0, At, B0); PG8_MMA(1, 1, At, B1); PG8_MMA_S(); PG8_BAR; PG8_SCHED;
	s_setprio 0
	s_add_i32 s68, 0, 0x20000
	v_lshl_add_u64 v[216:217], s[66:67], 0, v[198:199]
	s_add_i32 s66, s69, s18
	v_add_u32_e32 v74, s68, v221
	v_add_u32_e32 v75, s68, v222
	s_mov_b32 m0, s66
	ds_read_b128 v[66:69], v223 offset:16384
	ds_read_b128 v[70:73], v223 offset:17408
	ds_read_b128 v[224:227], v223 offset:18432
	ds_read_b128 v[228:231], v223 offset:19456
	ds_read_b128 v[232:235], v223 offset:20480
	ds_read_b128 v[240:243], v223 offset:21504
	ds_read_b128 v[244:247], v223 offset:22528
	ds_read_b128 v[248:251], v223 offset:23552
	ds_read_b128 v[166:169], v74
	ds_read_b128 v[170:173], v75
	global_load_lds_dwordx4 v[216:217], off
	v_lshl_add_u64 v[74:75], v[216:217], 0, s[64:65]
	s_add_i32 m0, s66, 0x2000
	s_add_i32 s13, s13, s18
	global_load_lds_dwordx4 v[74:75], off
	v_lshl_add_u64 v[74:75], v[216:217], 0, s[0:1]
	s_mov_b32 m0, s13
	v_lshl_add_u64 v[218:219], s[40:41], 0, v[196:197]
	global_load_lds_dwordx4 v[74:75], off
	v_lshl_add_u64 v[74:75], v[216:217], 0, s[74:75]
	s_add_i32 m0, s13, 0x2000
	s_nop 0
	global_load_lds_dwordx4 v[74:75], off
	s_mov_b32 m0, s19
	v_lshl_add_u64 v[74:75], v[218:219], 0, s[64:65]
	global_load_lds_dwordx4 v[218:219], off
	s_mov_b32 m0, s52
	s_nop 0
	global_load_lds_dwordx4 v[74:75], off
	s_waitcnt vmcnt(9)
	s_waitcnt lgkmcnt(0)
	s_setprio 1
	s_barrier
	v_mfma_f32_16x16x32_bf16 v[74:77], v[154:157], v[66:69], v[86:89]
	v_mfma_f32_16x16x32_bf16 v[78:81], v[162:165], v[66:69], v[82:85]
	v_mfma_f32_16x16x32_bf16 v[54:57], v[154:157], v[224:227], v[54:57]
	v_mfma_f32_16x16x32_bf16 v[50:53], v[162:165], v[224:227], v[50:53]
	v_mfma_f32_16x16x32_bf16 v[38:41], v[154:157], v[232:235], v[38:41]
	v_mfma_f32_16x16x32_bf16 v[34:37], v[162:165], v[232:235], v[34:37]
	v_mfma_f32_16x16x32_bf16 v[22:25], v[154:157], v[244:247], v[22:25]
	v_mfma_f32_16x16x32_bf16 v[18:21], v[162:165], v[244:247], v[18:21]
	v_mfma_f32_16x16x32_bf16 v[74:77], v[158:161], v[70:73], v[74:77]
	v_mfma_f32_16x16x32_bf16 v[78:81], v[174:177], v[70:73], v[78:81]
	v_mfma_f32_16x16x32_bf16 v[54:57], v[158:161], v[228:231], v[54:57]
	v_mfma_f32_16x16x32_bf16 v[50:53], v[174:177], v[228:231], v[50:53]
	v_mfma_f32_16x16x32_bf16 v[38:41], v[158:161], v[240:243], v[38:41]
	v_mfma_f32_16x16x32_bf16 v[34:37], v[174:177], v[240:243], v[34:37]
	v_mfma_f32_16x16x32_bf16 v[22:25], v[158:161], v[248:251], v[22:25]
	v_mfma_f32_16x16x32_bf16 v[18:21], v[174:177], v[248:251], v[18:21]
	v_mfma_f32_16x16x32_bf16 v[62:65], v[184:187], v[66:69], v[62:65]
	v_mfma_f32_16x16x32_bf16 v[58:61], v[192:195], v[66:69], v[58:61]
	v_mfma_f32_16x16x32_bf16 v[46:49], v[184:187], v[224:227], v[46:49]
	v_mfma_f32_16x16x32_bf16 v[42:45], v[192:195], v[224:227], v[42:45]
	v_mfma_f32_16x16x32_bf16 v[30:33], v[184:187], v[232:235], v[30:33]
	v_mfma_f32_16x16x32_bf16 v[26:29], v[192:195], v[232:235], v[26:29]
	v_mfma_f32_16x16x32_bf16 v[14:17], v[184:187], v[244:247], v[14:17]
	v_mfma_f32_16x16x32_bf16 v[10:13], v[192:195], v[244:247], v[10:13]
	v_mfma_f32_16x16x32_bf16 v[62:65], v[188:191], v[70:73], v[62:65]
	v_mfma_f32_16x16x32_bf16 v[58:61], v[180:183], v[70:73], v[58:61]
	v_mfma_f32_16x16x32_bf16 v[46:49], v[188:191], v[228:231], v[46:49]
	v_mfma_f32_16x16x32_bf16 v[42:45], v[180:183], v[228:231], v[42:45]
	v_mfma_f32_16x16x32_bf16 v[30:33], v[188:191], v[240:243], v[30:33]
	v_mfma_f32_16x16x32_bf16 v[26:29], v[180:183], v[240:243], v[26:29]
	v_mfma_f32_16x16x32_bf16 v[14:17], v[188:191], v[248:251], v[14:17]
	v_mfma_f32_16x16x32_bf16 v[10:13], v[180:183], v[248:251], v[10:13]
	s_setprio 0
	s_setprio 1
	v_cndmask_b32_e64 v66, 0, 1, s[82:83]
	v_cmp_ne_u32_e64 s[40:41], 1, v66
	s_andn2_b64 vcc, exec, s[82:83]
	s_mov_b64 s[94:95], -1
	s_cbranch_vccnz .LBB0_813
	v_mfma_f32_16x16x32_bf16 v[66:69], v[184:187], v[166:169], v[6:9]
	s_mov_b64 s[94:95], 0
	v_mfma_f32_16x16x32_bf16 v[70:73], v[192:195], v[166:169], v[2:5]
	v_mfma_f32_16x16x32_bf16 v[66:69], v[188:191], v[170:173], v[66:69]
	v_mfma_f32_16x16x32_bf16 v[70:73], v[180:183], v[170:173], v[70:73]

; #define PG8_STAGE(bufoff, gbase, voff) do { _Pragma("unroll") for (int _i = 0; _i < 2; ++_i) \
;         __builtin_amdgcn_global_load_lds((const unsigned*)((const char*)(gbase) + (size_t)_i * qstep + (voff)[0]), (PG8_LAS unsigned*)(lds + (bufoff) + ldsw + _i * 8192), 16, 0, 0); } while (0)
; #define PG8_LDA(dst, b, h) do { _Pragma("unroll") for (int m = 0; m < 4; ++m) _Pragma("unroll") for (int k = 0; k < 2; ++k) dst[m][k] = *(const PG8_LAS bf16x8*)(lds + PG8_SA(b, h) + aoff + m * 2048 + k * 1024); } while (0)
; #define PG8_LDB(dst, b, h) do { _Pragma("unroll") for (int n = 0; n < 2; ++n) _Pragma("unroll") for (int k = 0; k < 2; ++k) dst[n][k] = *(const PG8_LAS bf16x8*)(lds + PG8_SB(b, h) + boff + n * 2048 + k * 1024); } while (0)
; #define PG8_MMA(ai, bj, At, Bt) do { __builtin_amdgcn_s_setprio(1); _Pragma("unroll") for (int m = 0; m < 4; ++m) _Pragma("unroll") for (int n = 0; n < 2; ++n) _Pragma("unroll") for (int k = 0; k < 2; ++k) \
;         acc[ai][bj][m][n] = __builtin_amdgcn_mfma_f32_16x16x32_bf16(Bt[n][k], At[m][k], acc[ai][bj][m][n], 0, 0, 0); __builtin_amdgcn_s_setprio(0); } while (0)
; #define PG8_WAIT_V89() do { if constexpr (SLIVER) PG8_WAIT_V(9); else PG8_WAIT_V(8); } while (0)
; #define PG8_STAGE_S(b, gbase) do { if constexpr (SLIVER) __builtin_amdgcn_global_load_lds((const unsigned*)((const char*)(gbase) + voffS), (PG8_LAS unsigned*)(lds + STAGE_BYTES + (b) * 2048 + wid * 256), 4, 0, 0); } while (0)
; #define PG8_WAIT_L(n) asm volatile("s_waitcnt lgkmcnt(" #n ")" ::: "memory")
; #define PG8_BAR __builtin_amdgcn_s_barrier()
; #define PG8_SCHED __builtin_amdgcn_sched_barrier(0)
; template <class Epi, class Sched, bool ALIGN_EPI = false, bool SP2 = false, bool SLIVER = false>
; __device__ __forceinline__ void gemm_phase(PG8_LAS unsigned char* lds, const Gemm g, const Sched& S, const Epi& E) {
;     ...
;             PG8_LDB(B0, 1, 0); PG8_LDB(B1, 1, 1); PG8_SCHED; PG8_LDA(At, 1, 0); PG8_STAGE(PG8_SA(0, 1), a2 + hstep, voffA); PG8_STAGE_S(0, s2);
;             PG8_WAIT_V89(); PG8_WAIT_L(0); PG8_BAR; PG8_MMA(0, 0, At, B0); PG8_MMA(0, 1, At, B1); PG8_BAR; PG8_SCHED;
.LBB0_815:
	s_add_u32 s13, s92, s62
	s_addc_u32 s66, s93, s63
	s_add_u32 s13, s13, 0x100
	s_addc_u32 s68, s66, 0
	s_and_b64 s[66:67], s[80:81], exec
	s_cselect_b32 s67, s89, s68
	s_cselect_b32 s66, s88, s13
	s_barrier
	s_setprio 0
	s_add_i32 s13, 0, 0x18000
	v_add_u32_e32 v2, s13, v220
	s_add_i32 s68, 0, 0x1c000
	ds_read_b128 v[154:157], v2
	ds_read_b128 v[158:161], v2 offset:1024
	ds_read_b128 v[162:165], v2 offset:2048
	ds_read_b128 v[174:177], v2 offset:3072
	v_add_u32_e32 v2, s68, v220
	ds_read_b128 v[184:187], v2
	ds_read_b128 v[188:191], v2 offset:1024
	ds_read_b128 v[192:195], v2 offset:2048
	ds_read_b128 v[180:183], v2 offset:3072
	s_mov_b32 m0, s53
	v_lshl_add_u64 v[166:167], v[218:219], 0, s[0:1]
	ds_read_b128 v[2:5], v223 offset:32768
	ds_read_b128 v[6:9], v223 offset:33792
	ds_read_b128 v[82:85], v223 offset:34816
	ds_read_b128 v[86:89], v223 offset:35840
	ds_read_b128 v[224:227], v223 offset:36864
	ds_read_b128 v[228:231], v223 offset:37888
	ds_read_b128 v[232:235], v223 offset:38912
	ds_read_b128 v[240:243], v223 offset:39936
	global_load_lds_dwordx4 v[166:167], off
	v_lshl_add_u64 v[166:167], v[218:219], 0, s[74:75]
	s_mov_b32 m0, s54
	s_nop 0
	global_load_lds_dwordx4 v[166:167], off
	v_lshl_add_u64 v[166:167], s[66:67], 0, v[200:201]
	s_mov_b32 m0, s55
	s_nop 0
	global_load_lds_dword v[166:167], off
	s_waitcnt vmcnt(9)
	s_waitcnt lgkmcnt(0)
	s_setprio 1
	s_barrier
	v_mfma_f32_16x16x32_bf16 v[146:149], v[154:157], v[2:5], v[146:149]
	v_mfma_f32_16x16x32_bf16 v[170:173], v[158:161], v[6:9], v[146:149]
	v_mfma_f32_16x16x32_bf16 v[146:149], v[162:165], v[2:5], v[150:153]
	v_mfma_f32_16x16x32_bf16 v[134:137], v[154:157], v[82:85], v[134:137]
	v_mfma_f32_16x16x32_bf16 v[130:133], v[162:165], v[82:85], v[130:133]
	v_mfma_f32_16x16x32_bf16 v[118:121], v[154:157], v[224:227], v[118:121]
	v_mfma_f32_16x16x32_bf16 v[114:117], v[162:165], v[224:227], v[114:117]
	v_mfma_f32_16x16x32_bf16 v[102:105], v[154:157], v[232:235], v[102:105]
	v_mfma_f32_16x16x32_bf16 v[98:101], v[162:165], v[232:235], v[98:101]
	v_mfma_f32_16x16x32_bf16 v[166:169], v[174:177], v[6:9], v[146:149]
	v_mfma_f32_16x16x32_bf16 v[134:137], v[158:161], v[86:89], v[134:137]
	v_mfma_f32_16x16x32_bf16 v[130:133], v[174:177], v[86:89], v[130:133]
	v_mfma_f32_16x16x32_bf16 v[118:121], v[158:161], v[228:231], v[118:121]
	v_mfma_f32_16x16x32_bf16 v[114:117], v[174:177], v[228:231], v[114:117]
	v_mfma_f32_16x16x32_bf16 v[102:105], v[158:161], v[240:243], v[102:105]
	v_mfma_f32_16x16x32_bf16 v[98:101], v[174:177], v[240:243], v[98:101]
	v_mfma_f32_16x16x32_bf16 v[142:145], v[184:187], v[2:5], v[142:145]
	v_mfma_f32_16x16x32_bf16 v[2:5], v[192:195], v[2:5], v[138:141]
	v_mfma_f32_16x16x32_bf16 v[138:141], v[180:183], v[6:9], v[2:5]
	v_mfma_f32_16x16x32_bf16 v[2:5], v[184:187], v[82:85], v[126:129]
	v_mfma_f32_16x16x32_bf16 v[126:129], v[188:191], v[86:89], v[2:5]
	v_mfma_f32_16x16x32_bf16 v[2:5], v[192:195], v[82:85], v[122:125]
	v_mfma_f32_16x16x32_bf16 v[122:125], v[180:183], v[86:89], v[2:5]
	v_mfma_f32_16x16x32_bf16 v[2:5], v[184:187], v[224:227], v[110:113]
	v_mfma_f32_16x16x32_bf16 v[110:113], v[188:191], v[228:231], v[2:5]
	v_mfma_f32_16x16x32_bf16 v[2:5], v[192:195], v[224:227], v[106:109]
	v_mfma_f32_16x16x32_bf16 v[106:109], v[180:183], v[228:231], v[2:5]
	v_mfma_f32_16x16x32_bf16 v[2:5], v[184:187], v[232:235], v[94:97]
	v_mfma_f32_16x16x32_bf16 v[94:97], v[188:191], v[240:243], v[2:5]
	v_mfma_f32_16x16x32_bf16 v[2:5], v[192:195], v[232:235], v[90:93]
	v_mfma_f32_16x16x32_bf16 v[142:145], v[188:191], v[6:9], v[142:145]
	v_mfma_f32_16x16x32_bf16 v[90:93], v[180:183], v[240:243], v[2:5]
	s_barrier
; #define PG8_SB(B) __builtin_amdgcn_rcpf(1.f + expneg(B))
; #define PG8_SB(B) __builtin_amdgcn_rcpf(1.f + expneg(B))
; #define PG8_STAGE(bufoff, gbase, voff) do { _Pragma("unroll") for (int _i = 0; _i < 2; ++_i) \
;         __builtin_amdgcn_global_load_lds((const unsigned*)((const char*)(gbase) + (size_t)_i * qstep + (voff)[0]), (PG8_LAS unsigned*)(lds + (bufoff) + ldsw + _i * 8192), 16, 0, 0); } while (0)
; #define PG8_LDA(dst, b, h) do { _Pragma("unroll") for (int m = 0; m < 4; ++m) _Pragma("unroll") for (int k = 0; k < 2; ++k) dst[m][k] = *(const PG8_LAS bf16x8*)(lds + PG8_SA(b, h) + aoff + m * 2048 + k * 1024); } while (0)
; #define PG8_MMA(ai, bj, At, Bt) do { __builtin_amdgcn_s_setprio(1); _Pragma("unroll") for (int m = 0; m < 4; ++m) _Pragma("unroll") for (int n = 0; n < 2; ++n) _Pragma("unroll") for (int k = 0; k < 2; ++k) \
;         acc[ai][bj][m][n] = __builtin_amdgcn_mfma_f32_16x16x32_bf16(Bt[n][k], At[m][k], acc[ai][bj][m][n], 0, 0, 0); __builtin_amdgcn_s_setprio(0); } while (0)
; #define PG8_WAIT_V89() do { if constexpr (SLIVER) PG8_WAIT_V(9); else PG8_WAIT_V(8); } while (0)
; #define PG8_LDS_S(b) do { if constexpr (SLIVER) { Sf[0] = *(const PG8_LAS bf16x8*)(lds + STAGE_BYTES + (b) * 2048 + soff0); Sf[1] = *(const PG8_LAS bf16x8*)(lds + STAGE_BYTES + (b) * 2048 + (soff0 ^ 64)); } } while (0)
; #define PG8_WAIT_L(n) asm volatile("s_waitcnt lgkmcnt(" #n ")" ::: "memory")
; #define PG8_BAR __builtin_amdgcn_s_barrier()
; #define PG8_SCHED __builtin_amdgcn_sched_barrier(0)
; template <class Epi, class Sched, bool ALIGN_EPI = false, bool SP2 = false, bool SLIVER = false>
; __device__ __forceinline__ void gemm_phase(PG8_LAS unsigned char* lds, const Gemm g, const Sched& S, const Epi& E) {
;     ...
;             PG8_LDA(At, 1, 1); PG8_LDS_S(1); PG8_STAGE(PG8_SB(1, 0), b3, voffB); PG8_STAGE(PG8_SB(1, 1), b3 + hstep, voffB); PG8_STAGE(PG8_SA(1, 0), a3, voffA);
;             PG8_WAIT_V89(); PG8_WAIT_L(0); PG8_BAR; PG8_MMA(1, 0, At, B0); PG8_MMA(1, 1, At, B1); PG8_MMA_S(); PG8_BAR; PG8_SCHED;
	s_setprio 0
	s_add_i32 s66, 0, 0x20800
	v_add_u32_e32 v82, s66, v221
	v_add_u32_e32 v83, s66, v222
	s_add_i32 s13, s13, s18
	ds_read_b128 v[2:5], v223 offset:49152
	ds_read_b128 v[6:9], v223 offset:50176
	ds_read_b128 v[224:227], v223 offset:51200
	ds_read_b128 v[228:231], v223 offset:52224
	ds_read_b128 v[232:235], v223 offset:53248
	ds_read_b128 v[240:243], v223 offset:54272
	ds_read_b128 v[244:247], v223 offset:55296
	ds_read_b128 v[248:251], v223 offset:56320
	ds_read_b128 v[146:149], v82
	ds_read_b128 v[150:153], v83
	v_lshl_add_u64 v[82:83], v[216:217], 0, s[26:27]
	s_mov_b32 m0, s13
	s_mov_b64 s[66:67], 0x210080
	global_load_lds_dwordx4 v[82:83], off
	v_lshl_add_u64 v[82:83], v[216:217], 0, s[60:61]
	s_add_i32 m0, s13, 0x2000
	s_add_i32 s13, s68, s18
	global_load_lds_dwordx4 v[82:83], off
	v_lshl_add_u64 v[82:83], v[216:217], 0, s[8:9]
	s_mov_b32 m0, s13
	s_nop 0
	global_load_lds_dwordx4 v[82:83], off
	v_lshl_add_u64 v[82:83], v[216:217], 0, s[66:67]
	s_add_i32 m0, s13, 0x2000
	s_nop 0
	global_load_lds_dwordx4 v[82:83], off
	v_lshl_add_u64 v[82:83], v[218:219], 0, s[26:27]
	s_mov_b32 m0, s10
	s_nop 0
	global_load_lds_dwordx4 v[82:83], off
	v_lshl_add_u64 v[82:83], v[218:219], 0, s[60:61]
	s_mov_b32 m0, s48
	s_nop 0
	global_load_lds_dwordx4 v[82:83], off
	s_waitcnt vmcnt(9)
	s_waitcnt lgkmcnt(0)
	s_setprio 1
	s_barrier
	v_mfma_f32_16x16x32_bf16 v[74:77], v[154:157], v[2:5], v[74:77]
	v_mfma_f32_16x16x32_bf16 v[86:89], v[158:161], v[6:9], v[74:77]
	v_mfma_f32_16x16x32_bf16 v[74:77], v[162:165], v[2:5], v[78:81]
	v_mfma_f32_16x16x32_bf16 v[54:57], v[154:157], v[224:227], v[54:57]
	v_mfma_f32_16x16x32_bf16 v[50:53], v[162:165], v[224:227], v[50:53]
	v_mfma_f32_16x16x32_bf16 v[38:41], v[154:157], v[232:235], v[38:41]
	v_mfma_f32_16x16x32_bf16 v[34:37], v[162:165], v[232:235], v[34:37]
	v_mfma_f32_16x16x32_bf16 v[22:25], v[154:157], v[244:247], v[22:25]
	v_mfma_f32_16x16x32_bf16 v[18:21], v[162:165], v[244:247], v[18:21]
	v_mfma_f32_16x16x32_bf16 v[82:85], v[174:177], v[6:9], v[74:77]
	v_mfma_f32_16x16x32_bf16 v[54:57], v[158:161], v[228:231], v[54:57]
	v_mfma_f32_16x16x32_bf16 v[50:53], v[174:177], v[228:231], v[50:53]
	v_mfma_f32_16x16x32_bf16 v[38:41], v[158:161], v[240:243], v[38:41]
	v_mfma_f32_16x16x32_bf16 v[34:37], v[174:177], v[240:243], v[34:37]
	v_mfma_f32_16x16x32_bf16 v[22:25], v[158:161], v[248:251], v[22:25]
	v_mfma_f32_16x16x32_bf16 v[18:21], v[174:177], v[248:251], v[18:21]
	v_mfma_f32_16x16x32_bf16 v[62:65], v[184:187], v[2:5], v[62:65]
	v_mfma_f32_16x16x32_bf16 v[2:5], v[192:195], v[2:5], v[58:61]
	v_mfma_f32_16x16x32_bf16 v[58:61], v[180:183], v[6:9], v[2:5]
	v_mfma_f32_16x16x32_bf16 v[2:5], v[184:187], v[224:227], v[46:49]
	v_mfma_f32_16x16x32_bf16 v[46:49], v[188:191], v[228:231], v[2:5]
	v_mfma_f32_16x16x32_bf16 v[2:5], v[192:195], v[224:227], v[42:45]
	v_mfma_f32_16x16x32_bf16 v[42:45], v[180:183], v[228:231], v[2:5]
	v_mfma_f32_16x16x32_bf16 v[2:5], v[184:187], v[232:235], v[30:33]
	v_mfma_f32_16x16x32_bf16 v[30:33], v[188:191], v[240:243], v[2:5]
	v_mfma_f32_16x16x32_bf16 v[2:5], v[192:195], v[232:235], v[26:29]
	v_mfma_f32_16x16x32_bf16 v[26:29], v[180:183], v[240:243], v[2:5]
	v_mfma_f32_16x16x32_bf16 v[2:5], v[184:187], v[244:247], v[14:17]
	v_mfma_f32_16x16x32_bf16 v[14:17], v[188:191], v[248:251], v[2:5]
	v_mfma_f32_16x16x32_bf16 v[2:5], v[192:195], v[244:247], v[10:13]
	v_mfma_f32_16x16x32_bf16 v[62:65], v[188:191], v[6:9], v[62:65]
	v_mfma_f32_16x16x32_bf16 v[10:13], v[180:183], v[248:251], v[2:5]
	s_setprio 0
	s_setprio 1
	s_and_b64 vcc, exec, s[40:41]
	s_mov_b64 s[40:41], -1
	s_cbranch_vccnz .LBB0_817
	v_mfma_f32_16x16x32_bf16 v[2:5], v[184:187], v[146:149], v[66:69]
	s_mov_b64 s[40:41], 0
	v_mfma_f32_16x16x32_bf16 v[6:9], v[188:191], v[150:153], v[2:5]
	v_mfma_f32_16x16x32_bf16 v[2:5], v[192:195], v[146:149], v[70:73]
	v_mfma_f32_16x16x32_bf16 v[2:5], v[180:183], v[150:153], v[2:5]

; #define PG8_STAGE(bufoff, gbase, voff) do { _Pragma("unroll") for (int _i = 0; _i < 2; ++_i) \
;         __builtin_amdgcn_global_load_lds((const unsigned*)((const char*)(gbase) + (size_t)_i * qstep + (voff)[0]), (PG8_LAS unsigned*)(lds + (bufoff) + ldsw + _i * 8192), 16, 0, 0); } while (0)
; #define PG8_LDA(dst, b, h) do { _Pragma("unroll") for (int m = 0; m < 4; ++m) _Pragma("unroll") for (int k = 0; k < 2; ++k) dst[m][k] = *(const PG8_LAS bf16x8*)(lds + PG8_SA(b, h) + aoff + m * 2048 + k * 1024); } while (0)
; #define PG8_LDB(dst, b, h) do { _Pragma("unroll") for (int n = 0; n < 2; ++n) _Pragma("unroll") for (int k = 0; k < 2; ++k) dst[n][k] = *(const PG8_LAS bf16x8*)(lds + PG8_SB(b, h) + boff + n * 2048 + k * 1024); } while (0)
; #define PG8_MMA(ai, bj, At, Bt) do { __builtin_amdgcn_s_setprio(1); _Pragma("unroll") for (int m = 0; m < 4; ++m) _Pragma("unroll") for (int n = 0; n < 2; ++n) _Pragma("unroll") for (int k = 0; k < 2; ++k) \
;         acc[ai][bj][m][n] = __builtin_amdgcn_mfma_f32_16x16x32_bf16(Bt[n][k], At[m][k], acc[ai][bj][m][n], 0, 0, 0); __builtin_amdgcn_s_setprio(0); } while (0)
; #define PG8_WAIT_V89() do { if constexpr (SLIVER) PG8_WAIT_V(9); else PG8_WAIT_V(8); } while (0)
; #define PG8_STAGE_S(b, gbase) do { if constexpr (SLIVER) __builtin_amdgcn_global_load_lds((const unsigned*)((const char*)(gbase) + voffS), (PG8_LAS unsigned*)(lds + STAGE_BYTES + (b) * 2048 + wid * 256), 4, 0, 0); } while (0)
; #define PG8_WAIT_L(n) asm volatile("s_waitcnt lgkmcnt(" #n ")" ::: "memory")
; #define PG8_BAR __builtin_amdgcn_s_barrier()
; #define PG8_SCHED __builtin_amdgcn_sched_barrier(0)
; template <class Epi, class Sched, bool ALIGN_EPI = false, bool SP2 = false, bool SLIVER = false>
; __device__ __forceinline__ void gemm_phase(PG8_LAS unsigned char* lds, const Gemm g, const Sched& S, const Epi& E) {
;     ...
;             PG8_LDB(B0, 0, 0); PG8_LDB(B1, 0, 1); PG8_SCHED; PG8_LDA(At, 0, 0); PG8_STAGE(PG8_SA(1, 1), a1 + hstep, voffA); PG8_STAGE_S(1, s1);
;             PG8_WAIT_V89(); PG8_WAIT_L(0); PG8_BAR; PG8_MMA(0, 0, At, B0); PG8_MMA(0, 1, At, B1); PG8_BAR; PG8_SCHED;
.LBB0_934:
	s_cmp_eq_u32 s66, s62
	s_cselect_b64 s[80:81], -1, 0
	s_add_u32 s12, s42, s62
	s_addc_u32 s13, s43, s63
	s_add_u32 s40, s12, 0x100
	s_addc_u32 s41, s13, 0
	s_and_b64 s[12:13], s[80:81], exec
	s_cselect_b32 s41, s95, s41
	s_cselect_b32 s40, s94, s40
	s_add_u32 s68, s17, s62
	s_addc_u32 s69, s45, s63
	s_add_i32 s76, 0, 0x10000
	s_and_b64 s[12:13], s[80:81], exec
	v_add_u32_e32 v138, s76, v212
	s_cselect_b32 s13, s97, s69
	s_cselect_b32 s12, s96, s68
	s_add_i32 s68, 0, 0x14000
	ds_read_b128 v[146:149], v138
	ds_read_b128 v[150:153], v138 offset:1024
	ds_read_b128 v[154:157], v138 offset:2048
	ds_read_b128 v[158:161], v138 offset:3072
	v_add_u32_e32 v138, s68, v212
	ds_read_b128 v[166:169], v138
	ds_read_b128 v[170:173], v138 offset:1024
	ds_read_b128 v[174:177], v138 offset:2048
	ds_read_b128 v[162:165], v138 offset:3072
	v_lshl_add_u64 v[202:203], v[198:199], 0, s[62:63]
	s_mov_b64 vcc, 0x90080
	v_lshl_add_u64 v[208:209], v[202:203], 0, vcc
	s_add_i32 m0, s93, 0xc000
	s_mov_b64 vcc, 0xd8080
	ds_read_b128 v[138:141], v215
	ds_read_b128 v[142:145], v215 offset:1024
	ds_read_b128 v[180:183], v215 offset:2048
	ds_read_b128 v[184:187], v215 offset:3072
	ds_read_b128 v[216:219], v215 offset:4096
	ds_read_b128 v[220:223], v215 offset:5120
	ds_read_b128 v[224:227], v215 offset:6144
	ds_read_b128 v[228:231], v215 offset:7168
	global_load_lds_dwordx4 v[208:209], off
	v_lshl_add_u64 v[202:203], v[202:203], 0, vcc
	s_add_i32 m0, s93, 0xe000
	s_nop 0
	global_load_lds_dwordx4 v[202:203], off
	v_lshl_add_u64 v[202:203], v[200:201], 0, s[62:63]
	s_add_i32 m0, s50, 0x20800
	s_nop 0
	global_load_lds_dword v[202:203], off
	s_waitcnt vmcnt(9)
	s_waitcnt lgkmcnt(0)
	s_setprio 1
	s_barrier
	v_mfma_f32_16x16x32_bf16 v[134:137], v[146:149], v[138:141], v[134:137]
	v_mfma_f32_16x16x32_bf16 v[130:133], v[154:157], v[138:141], v[130:133]
	v_mfma_f32_16x16x32_bf16 v[126:129], v[146:149], v[180:183], v[126:129]
	v_mfma_f32_16x16x32_bf16 v[122:125], v[154:157], v[180:183], v[122:125]
	v_mfma_f32_16x16x32_bf16 v[114:117], v[146:149], v[216:219], v[114:117]
	v_mfma_f32_16x16x32_bf16 v[106:109], v[154:157], v[216:219], v[106:109]
	v_mfma_f32_16x16x32_bf16 v[98:101], v[146:149], v[224:227], v[98:101]
	v_mfma_f32_16x16x32_bf16 v[90:93], v[154:157], v[224:227], v[90:93]
	v_mfma_f32_16x16x32_bf16 v[134:137], v[150:153], v[142:145], v[134:137]
	v_mfma_f32_16x16x32_bf16 v[130:133], v[158:161], v[142:145], v[130:133]
	v_mfma_f32_16x16x32_bf16 v[126:129], v[150:153], v[184:187], v[126:129]
	v_mfma_f32_16x16x32_bf16 v[122:125], v[158:161], v[184:187], v[122:125]
	v_mfma_f32_16x16x32_bf16 v[114:117], v[150:153], v[220:223], v[114:117]
	v_mfma_f32_16x16x32_bf16 v[106:109], v[158:161], v[220:223], v[106:109]
	v_mfma_f32_16x16x32_bf16 v[98:101], v[150:153], v[228:231], v[98:101]
	v_mfma_f32_16x16x32_bf16 v[90:93], v[158:161], v[228:231], v[90:93]
	v_mfma_f32_16x16x32_bf16 v[118:121], v[166:169], v[138:141], v[118:121]
	v_mfma_f32_16x16x32_bf16 v[110:113], v[174:177], v[138:141], v[110:113]
	v_mfma_f32_16x16x32_bf16 v[102:105], v[166:169], v[180:183], v[102:105]
	v_mfma_f32_16x16x32_bf16 v[94:97], v[174:177], v[180:183], v[94:97]
	v_mfma_f32_16x16x32_bf16 v[86:89], v[166:169], v[216:219], v[86:89]
	v_mfma_f32_16x16x32_bf16 v[82:85], v[174:177], v[216:219], v[82:85]
	v_mfma_f32_16x16x32_bf16 v[78:81], v[166:169], v[224:227], v[78:81]
	v_mfma_f32_16x16x32_bf16 v[74:77], v[174:177], v[224:227], v[74:77]
	v_mfma_f32_16x16x32_bf16 v[118:121], v[170:173], v[142:145], v[118:121]
	v_mfma_f32_16x16x32_bf16 v[110:113], v[162:165], v[142:145], v[110:113]
	v_mfma_f32_16x16x32_bf16 v[102:105], v[170:173], v[184:187], v[102:105]
	v_mfma_f32_16x16x32_bf16 v[94:97], v[162:165], v[184:187], v[94:97]
	v_mfma_f32_16x16x32_bf16 v[86:89], v[170:173], v[220:223], v[86:89]
	v_mfma_f32_16x16x32_bf16 v[82:85], v[162:165], v[220:223], v[82:85]
	v_mfma_f32_16x16x32_bf16 v[78:81], v[170:173], v[228:231], v[78:81]
	v_mfma_f32_16x16x32_bf16 v[74:77], v[162:165], v[228:231], v[74:77]
	s_barrier
; #define PG8_SB(B) __builtin_amdgcn_rcpf(1.f + expneg(B))
; #define PG8_SB(B) __builtin_amdgcn_rcpf(1.f + expneg(B))
; #define PG8_STAGE(bufoff, gbase, voff) do { _Pragma("unroll") for (int _i = 0; _i < 2; ++_i) \
;         __builtin_amdgcn_global_load_lds((const unsigned*)((const char*)(gbase) + (size_t)_i * qstep + (voff)[0]), (PG8_LAS unsigned*)(lds + (bufoff) + ldsw + _i * 8192), 16, 0, 0); } while (0)
; #define PG8_LDA(dst, b, h) do { _Pragma("unroll") for (int m = 0; m < 4; ++m) _Pragma("unroll") for (int k = 0; k < 2; ++k) dst[m][k] = *(const PG8_LAS bf16x8*)(lds + PG8_SA(b, h) + aoff + m * 2048 + k * 1024); } while (0)
; #define PG8_MMA(ai, bj, At, Bt) do { __builtin_amdgcn_s_setprio(1); _Pragma("unroll") for (int m = 0; m < 4; ++m) _Pragma("unroll") for (int n = 0; n < 2; ++n) _Pragma("unroll") for (int k = 0; k < 2; ++k) \
;         acc[ai][bj][m][n] = __builtin_amdgcn_mfma_f32_16x16x32_bf16(Bt[n][k], At[m][k], acc[ai][bj][m][n], 0, 0, 0); __builtin_amdgcn_s_setprio(0); } while (0)
; #define PG8_WAIT_V89() do { if constexpr (SLIVER) PG8_WAIT_V(9); else PG8_WAIT_V(8); } while (0)
; #define PG8_LDS_S(b) do { if constexpr (SLIVER) { Sf[0] = *(const PG8_LAS bf16x8*)(lds + STAGE_BYTES + (b) * 2048 + soff0); Sf[1] = *(const PG8_LAS bf16x8*)(lds + STAGE_BYTES + (b) * 2048 + (soff0 ^ 64)); } } while (0)
; #define PG8_WAIT_L(n) asm volatile("s_waitcnt lgkmcnt(" #n ")" ::: "memory")
; #define PG8_BAR __builtin_amdgcn_s_barrier()
; #define PG8_SCHED __builtin_amdgcn_sched_barrier(0)
; template <class Epi, class Sched, bool ALIGN_EPI = false, bool SP2 = false, bool SLIVER = false>
; __device__ __forceinline__ void gemm_phase(PG8_LAS unsigned char* lds, const Gemm g, const Sched& S, const Epi& E) {
;     ...
;             PG8_LDA(At, 0, 1); PG8_LDS_S(0); PG8_STAGE(PG8_SB(0, 0), b2, voffB); PG8_STAGE(PG8_SB(0, 1), b2 + hstep, voffB); PG8_STAGE(PG8_SA(0, 0), a2, voffA);
;             PG8_WAIT_V89(); PG8_WAIT_L(0); PG8_BAR; PG8_MMA(1, 0, At, B0); PG8_MMA(1, 1, At, B1); PG8_MMA_S(); PG8_BAR; PG8_SCHED;
	s_setprio 0
	s_add_i32 s69, 0, 0x20000
	v_lshl_add_u64 v[202:203], s[12:13], 0, v[190:191]
	s_add_i32 s12, s76, s92
	v_add_u32_e32 v178, s69, v213
	v_add_u32_e32 v184, s69, v214
	s_mov_b32 m0, s12
	ds_read_b128 v[138:141], v215 offset:16384
	ds_read_b128 v[142:145], v215 offset:17408
	ds_read_b128 v[216:219], v215 offset:18432
	ds_read_b128 v[220:223], v215 offset:19456
	ds_read_b128 v[224:227], v215 offset:20480
	ds_read_b128 v[228:231], v215 offset:21504
	ds_read_b128 v[232:235], v215 offset:22528
	ds_read_b128 v[240:243], v215 offset:23552
	ds_read_b128 v[180:183], v178
	ds_read_b128 v[184:187], v184
	global_load_lds_dwordx4 v[202:203], off
	v_lshl_add_u64 v[208:209], v[202:203], 0, s[70:71]
	s_add_i32 m0, s12, 0x2000
	s_add_i32 s12, s68, s92
	global_load_lds_dwordx4 v[208:209], off
	v_lshl_add_u64 v[208:209], v[202:203], 0, s[46:47]
	s_mov_b32 m0, s12
	v_lshl_add_u64 v[210:211], s[40:41], 0, v[188:189]
	global_load_lds_dwordx4 v[208:209], off
	v_lshl_add_u64 v[208:209], v[202:203], 0, s[6:7]
	s_add_i32 m0, s12, 0x2000
	s_nop 0
	global_load_lds_dwordx4 v[208:209], off
	s_mov_b32 m0, s93
	v_lshl_add_u64 v[208:209], v[210:211], 0, s[70:71]
	global_load_lds_dwordx4 v[210:211], off
	s_mov_b32 m0, s48
	s_nop 0
	global_load_lds_dwordx4 v[208:209], off
	s_waitcnt vmcnt(9)
	s_waitcnt lgkmcnt(0)
	s_setprio 1
	s_barrier
	v_mfma_f32_16x16x32_bf16 v[70:73], v[146:149], v[138:141], v[70:73]
	v_mfma_f32_16x16x32_bf16 v[66:69], v[154:157], v[138:141], v[66:69]
	v_mfma_f32_16x16x32_bf16 v[62:65], v[146:149], v[216:219], v[62:65]
	v_mfma_f32_16x16x32_bf16 v[58:61], v[154:157], v[216:219], v[58:61]
	v_mfma_f32_16x16x32_bf16 v[50:53], v[146:149], v[224:227], v[50:53]
	v_mfma_f32_16x16x32_bf16 v[42:45], v[154:157], v[224:227], v[42:45]
	v_mfma_f32_16x16x32_bf16 v[34:37], v[146:149], v[232:235], v[34:37]
	v_mfma_f32_16x16x32_bf16 v[26:29], v[154:157], v[232:235], v[26:29]
	v_mfma_f32_16x16x32_bf16 v[70:73], v[150:153], v[142:145], v[70:73]
	v_mfma_f32_16x16x32_bf16 v[66:69], v[158:161], v[142:145], v[66:69]
	v_mfma_f32_16x16x32_bf16 v[62:65], v[150:153], v[220:223], v[62:65]
	v_mfma_f32_16x16x32_bf16 v[58:61], v[158:161], v[220:223], v[58:61]
	v_mfma_f32_16x16x32_bf16 v[50:53], v[150:153], v[228:231], v[50:53]
	v_mfma_f32_16x16x32_bf16 v[42:45], v[158:161], v[228:231], v[42:45]
	v_mfma_f32_16x16x32_bf16 v[34:37], v[150:153], v[240:243], v[34:37]
	v_mfma_f32_16x16x32_bf16 v[26:29], v[158:161], v[240:243], v[26:29]
	v_mfma_f32_16x16x32_bf16 v[54:57], v[166:169], v[138:141], v[54:57]
	v_mfma_f32_16x16x32_bf16 v[46:49], v[174:177], v[138:141], v[46:49]
	v_mfma_f32_16x16x32_bf16 v[38:41], v[166:169], v[216:219], v[38:41]
	v_mfma_f32_16x16x32_bf16 v[30:33], v[174:177], v[216:219], v[30:33]
	v_mfma_f32_16x16x32_bf16 v[22:25], v[166:169], v[224:227], v[22:25]
	v_mfma_f32_16x16x32_bf16 v[18:21], v[174:177], v[224:227], v[18:21]
	v_mfma_f32_16x16x32_bf16 v[14:17], v[166:169], v[232:235], v[14:17]
	v_mfma_f32_16x16x32_bf16 v[10:13], v[174:177], v[232:235], v[10:13]
	v_mfma_f32_16x16x32_bf16 v[54:57], v[170:173], v[142:145], v[54:57]
	v_mfma_f32_16x16x32_bf16 v[46:49], v[162:165], v[142:145], v[46:49]
	v_mfma_f32_16x16x32_bf16 v[38:41], v[170:173], v[220:223], v[38:41]
	v_mfma_f32_16x16x32_bf16 v[30:33], v[162:165], v[220:223], v[30:33]
	v_mfma_f32_16x16x32_bf16 v[22:25], v[170:173], v[228:231], v[22:25]
	v_mfma_f32_16x16x32_bf16 v[18:21], v[162:165], v[228:231], v[18:21]
	v_mfma_f32_16x16x32_bf16 v[14:17], v[170:173], v[240:243], v[14:17]
	v_mfma_f32_16x16x32_bf16 v[10:13], v[162:165], v[240:243], v[10:13]
	s_setprio 0
	s_setprio 1
	v_cndmask_b32_e64 v138, 0, 1, s[90:91]
	v_cmp_ne_u32_e64 s[40:41], 1, v138
	s_andn2_b64 vcc, exec, s[90:91]
	s_mov_b64 s[12:13], -1
	s_cbranch_vccnz .LBB0_936
	v_mfma_f32_16x16x32_bf16 v[138:141], v[166:169], v[180:183], v[6:9]
	s_mov_b64 s[12:13], 0
	v_mfma_f32_16x16x32_bf16 v[142:145], v[174:177], v[180:183], v[2:5]
	v_mfma_f32_16x16x32_bf16 v[138:141], v[170:173], v[184:187], v[138:141]
	v_mfma_f32_16x16x32_bf16 v[142:145], v[162:165], v[184:187], v[142:145]

; #define PG8_STAGE(bufoff, gbase, voff) do { _Pragma("unroll") for (int _i = 0; _i < 2; ++_i) \
;         __builtin_amdgcn_global_load_lds((const unsigned*)((const char*)(gbase) + (size_t)_i * qstep + (voff)[0]), (PG8_LAS unsigned*)(lds + (bufoff) + ldsw + _i * 8192), 16, 0, 0); } while (0)
; #define PG8_LDA(dst, b, h) do { _Pragma("unroll") for (int m = 0; m < 4; ++m) _Pragma("unroll") for (int k = 0; k < 2; ++k) dst[m][k] = *(const PG8_LAS bf16x8*)(lds + PG8_SA(b, h) + aoff + m * 2048 + k * 1024); } while (0)
; #define PG8_LDB(dst, b, h) do { _Pragma("unroll") for (int n = 0; n < 2; ++n) _Pragma("unroll") for (int k = 0; k < 2; ++k) dst[n][k] = *(const PG8_LAS bf16x8*)(lds + PG8_SB(b, h) + boff + n * 2048 + k * 1024); } while (0)
; #define PG8_MMA(ai, bj, At, Bt) do { __builtin_amdgcn_s_setprio(1); _Pragma("unroll") for (int m = 0; m < 4; ++m) _Pragma("unroll") for (int n = 0; n < 2; ++n) _Pragma("unroll") for (int k = 0; k < 2; ++k) \
;         acc[ai][bj][m][n] = __builtin_amdgcn_mfma_f32_16x16x32_bf16(Bt[n][k], At[m][k], acc[ai][bj][m][n], 0, 0, 0); __builtin_amdgcn_s_setprio(0); } while (0)
; #define PG8_WAIT_V89() do { if constexpr (SLIVER) PG8_WAIT_V(9); else PG8_WAIT_V(8); } while (0)
; #define PG8_STAGE_S(b, gbase) do { if constexpr (SLIVER) __builtin_amdgcn_global_load_lds((const unsigned*)((const char*)(gbase) + voffS), (PG8_LAS unsigned*)(lds + STAGE_BYTES + (b) * 2048 + wid * 256), 4, 0, 0); } while (0)
; #define PG8_WAIT_L(n) asm volatile("s_waitcnt lgkmcnt(" #n ")" ::: "memory")
; #define PG8_BAR __builtin_amdgcn_s_barrier()
; #define PG8_SCHED __builtin_amdgcn_sched_barrier(0)
; template <class Epi, class Sched, bool ALIGN_EPI = false, bool SP2 = false, bool SLIVER = false>
; __device__ __forceinline__ void gemm_phase(PG8_LAS unsigned char* lds, const Gemm g, const Sched& S, const Epi& E) {
;     ...
;             PG8_LDB(B0, 1, 0); PG8_LDB(B1, 1, 1); PG8_SCHED; PG8_LDA(At, 1, 0); PG8_STAGE(PG8_SA(0, 1), a2 + hstep, voffA); PG8_STAGE_S(0, s2);
;             PG8_WAIT_V89(); PG8_WAIT_L(0); PG8_BAR; PG8_MMA(0, 0, At, B0); PG8_MMA(0, 1, At, B1); PG8_BAR; PG8_SCHED;
.LBB0_938:
	s_add_u32 s12, s54, s62
	s_addc_u32 s13, s55, s63
	s_add_u32 s68, s12, 0x100
	s_addc_u32 s69, s13, 0
	s_and_b64 s[12:13], s[80:81], exec
	s_cselect_b32 s13, s19, s69
	s_cselect_b32 s12, s18, s68
	s_barrier
	s_setprio 0
	s_add_i32 s68, 0, 0x18000
	v_add_u32_e32 v2, s68, v212
	s_add_i32 s69, 0, 0x1c000
	ds_read_b128 v[146:149], v2
	ds_read_b128 v[150:153], v2 offset:1024
	ds_read_b128 v[154:157], v2 offset:2048
	ds_read_b128 v[158:161], v2 offset:3072
	v_add_u32_e32 v2, s69, v212
	ds_read_b128 v[166:169], v2
	ds_read_b128 v[170:173], v2 offset:1024
	ds_read_b128 v[174:177], v2 offset:2048
	ds_read_b128 v[162:165], v2 offset:3072
	s_mov_b32 m0, s49
	v_lshl_add_u64 v[208:209], v[210:211], 0, s[46:47]
	ds_read_b128 v[2:5], v215 offset:32768
	ds_read_b128 v[6:9], v215 offset:33792
	ds_read_b128 v[180:183], v215 offset:34816
	ds_read_b128 v[184:187], v215 offset:35840
	ds_read_b128 v[216:219], v215 offset:36864
	ds_read_b128 v[220:223], v215 offset:37888
	ds_read_b128 v[224:227], v215 offset:38912
	ds_read_b128 v[228:231], v215 offset:39936
	global_load_lds_dwordx4 v[208:209], off
	v_lshl_add_u64 v[208:209], v[210:211], 0, s[6:7]
	s_mov_b32 m0, s88
	s_nop 0
	global_load_lds_dwordx4 v[208:209], off
	v_lshl_add_u64 v[208:209], s[12:13], 0, v[192:193]
	s_mov_b32 m0, s89
	s_nop 0
	global_load_lds_dword v[208:209], off
	s_waitcnt vmcnt(9)
	s_waitcnt lgkmcnt(0)
	s_setprio 1
	s_barrier
	v_mfma_f32_16x16x32_bf16 v[134:137], v[146:149], v[2:5], v[134:137]
	v_mfma_f32_16x16x32_bf16 v[130:133], v[154:157], v[2:5], v[130:133]
	v_mfma_f32_16x16x32_bf16 v[126:129], v[146:149], v[180:183], v[126:129]
	v_mfma_f32_16x16x32_bf16 v[122:125], v[154:157], v[180:183], v[122:125]
	v_mfma_f32_16x16x32_bf16 v[114:117], v[146:149], v[216:219], v[114:117]
	v_mfma_f32_16x16x32_bf16 v[106:109], v[154:157], v[216:219], v[106:109]
	v_mfma_f32_16x16x32_bf16 v[98:101], v[146:149], v[224:227], v[98:101]
	v_mfma_f32_16x16x32_bf16 v[90:93], v[154:157], v[224:227], v[90:93]
	v_mfma_f32_16x16x32_bf16 v[134:137], v[150:153], v[6:9], v[134:137]
	v_mfma_f32_16x16x32_bf16 v[130:133], v[158:161], v[6:9], v[130:133]
	v_mfma_f32_16x16x32_bf16 v[126:129], v[150:153], v[184:187], v[126:129]
	v_mfma_f32_16x16x32_bf16 v[122:125], v[158:161], v[184:187], v[122:125]
	v_mfma_f32_16x16x32_bf16 v[114:117], v[150:153], v[220:223], v[114:117]
	v_mfma_f32_16x16x32_bf16 v[106:109], v[158:161], v[220:223], v[106:109]
	v_mfma_f32_16x16x32_bf16 v[98:101], v[150:153], v[228:231], v[98:101]
	v_mfma_f32_16x16x32_bf16 v[90:93], v[158:161], v[228:231], v[90:93]
	v_mfma_f32_16x16x32_bf16 v[118:121], v[166:169], v[2:5], v[118:121]
	v_mfma_f32_16x16x32_bf16 v[2:5], v[174:177], v[2:5], v[110:113]
	v_mfma_f32_16x16x32_bf16 v[110:113], v[162:165], v[6:9], v[2:5]
	v_mfma_f32_16x16x32_bf16 v[2:5], v[166:169], v[180:183], v[102:105]
	v_mfma_f32_16x16x32_bf16 v[102:105], v[170:173], v[184:187], v[2:5]
	v_mfma_f32_16x16x32_bf16 v[2:5], v[174:177], v[180:183], v[94:97]
	v_mfma_f32_16x16x32_bf16 v[94:97], v[162:165], v[184:187], v[2:5]
	v_mfma_f32_16x16x32_bf16 v[2:5], v[166:169], v[216:219], v[86:89]
	v_mfma_f32_16x16x32_bf16 v[86:89], v[170:173], v[220:223], v[2:5]
	v_mfma_f32_16x16x32_bf16 v[2:5], v[174:177], v[216:219], v[82:85]
	v_mfma_f32_16x16x32_bf16 v[82:85], v[162:165], v[220:223], v[2:5]
	v_mfma_f32_16x16x32_bf16 v[2:5], v[166:169], v[224:227], v[78:81]
	v_mfma_f32_16x16x32_bf16 v[78:81], v[170:173], v[228:231], v[2:5]
	v_mfma_f32_16x16x32_bf16 v[2:5], v[174:177], v[224:227], v[74:77]
	v_mfma_f32_16x16x32_bf16 v[118:121], v[170:173], v[6:9], v[118:121]
	v_mfma_f32_16x16x32_bf16 v[74:77], v[162:165], v[228:231], v[2:5]
	s_barrier
; #define PG8_SB(B) __builtin_amdgcn_rcpf(1.f + expneg(B))
; #define PG8_SB(B) __builtin_amdgcn_rcpf(1.f + expneg(B))
; #define PG8_STAGE(bufoff, gbase, voff) do { _Pragma("unroll") for (int _i = 0; _i < 2; ++_i) \
;         __builtin_amdgcn_global_load_lds((const unsigned*)((const char*)(gbase) + (size_t)_i * qstep + (voff)[0]), (PG8_LAS unsigned*)(lds + (bufoff) + ldsw + _i * 8192), 16, 0, 0); } while (0)
; #define PG8_LDA(dst, b, h) do { _Pragma("unroll") for (int m = 0; m < 4; ++m) _Pragma("unroll") for (int k = 0; k < 2; ++k) dst[m][k] = *(const PG8_LAS bf16x8*)(lds + PG8_SA(b, h) + aoff + m * 2048 + k * 1024); } while (0)
; #define PG8_MMA(ai, bj, At, Bt) do { __builtin_amdgcn_s_setprio(1); _Pragma("unroll") for (int m = 0; m < 4; ++m) _Pragma("unroll") for (int n = 0; n < 2; ++n) _Pragma("unroll") for (int k = 0; k < 2; ++k) \
;         acc[ai][bj][m][n] = __builtin_amdgcn_mfma_f32_16x16x32_bf16(Bt[n][k], At[m][k], acc[ai][bj][m][n], 0, 0, 0); __builtin_amdgcn_s_setprio(0); } while (0)
; #define PG8_WAIT_V89() do { if constexpr (SLIVER) PG8_WAIT_V(9); else PG8_WAIT_V(8); } while (0)
; #define PG8_LDS_S(b) do { if constexpr (SLIVER) { Sf[0] = *(const PG8_LAS bf16x8*)(lds + STAGE_BYTES + (b) * 2048 + soff0); Sf[1] = *(const PG8_LAS bf16x8*)(lds + STAGE_BYTES + (b) * 2048 + (soff0 ^ 64)); } } while (0)
; #define PG8_WAIT_L(n) asm volatile("s_waitcnt lgkmcnt(" #n ")" ::: "memory")
; #define PG8_BAR __builtin_amdgcn_s_barrier()
; #define PG8_SCHED __builtin_amdgcn_sched_barrier(0)
; template <class Epi, class Sched, bool ALIGN_EPI = false, bool SP2 = false, bool SLIVER = false>
; __device__ __forceinline__ void gemm_phase(PG8_LAS unsigned char* lds, const Gemm g, const Sched& S, const Epi& E) {
;     ...
;             PG8_LDA(At, 1, 1); PG8_LDS_S(1); PG8_STAGE(PG8_SB(1, 0), b3, voffB); PG8_STAGE(PG8_SB(1, 1), b3 + hstep, voffB); PG8_STAGE(PG8_SA(1, 0), a3, voffA);
;             PG8_WAIT_V89(); PG8_WAIT_L(0); PG8_BAR; PG8_MMA(1, 0, At, B0); PG8_MMA(1, 1, At, B1); PG8_MMA_S(); PG8_BAR; PG8_SCHED;
	s_setprio 0
	s_add_i32 s12, 0, 0x20800
	v_add_u32_e32 v178, s12, v213
	v_add_u32_e32 v184, s12, v214
	s_add_i32 s12, s68, s92
	v_lshl_add_u64 v[208:209], v[202:203], 0, s[26:27]
	s_mov_b32 m0, s12
	ds_read_b128 v[2:5], v215 offset:49152
	ds_read_b128 v[6:9], v215 offset:50176
	ds_read_b128 v[216:219], v215 offset:51200
	ds_read_b128 v[220:223], v215 offset:52224
	ds_read_b128 v[224:227], v215 offset:53248
	ds_read_b128 v[228:231], v215 offset:54272
	ds_read_b128 v[232:235], v215 offset:55296
	ds_read_b128 v[240:243], v215 offset:56320
	ds_read_b128 v[180:183], v178
	ds_read_b128 v[184:187], v184
	global_load_lds_dwordx4 v[208:209], off
	v_lshl_add_u64 v[208:209], v[202:203], 0, s[58:59]
	s_add_i32 m0, s12, 0x2000
	s_mov_b64 s[12:13], 0x90080
	global_load_lds_dwordx4 v[208:209], off
	v_lshl_add_u64 v[208:209], v[202:203], 0, s[12:13]
	s_add_i32 s12, s69, s92
	s_mov_b32 m0, s12
	s_mov_b64 s[68:69], 0xd8080
	global_load_lds_dwordx4 v[208:209], off
	v_lshl_add_u64 v[202:203], v[202:203], 0, s[68:69]
	s_add_i32 m0, s12, 0x2000
	s_nop 0
	global_load_lds_dwordx4 v[202:203], off
	v_lshl_add_u64 v[202:203], v[210:211], 0, s[26:27]
	s_mov_b32 m0, s51
	s_nop 0
	global_load_lds_dwordx4 v[202:203], off
	v_lshl_add_u64 v[202:203], v[210:211], 0, s[58:59]
	s_mov_b32 m0, s53
	s_nop 0
	global_load_lds_dwordx4 v[202:203], off
	s_waitcnt vmcnt(9)
	s_waitcnt lgkmcnt(0)
	s_setprio 1
	s_barrier
	v_mfma_f32_16x16x32_bf16 v[70:73], v[146:149], v[2:5], v[70:73]
	v_mfma_f32_16x16x32_bf16 v[66:69], v[154:157], v[2:5], v[66:69]
	v_mfma_f32_16x16x32_bf16 v[62:65], v[146:149], v[216:219], v[62:65]
	v_mfma_f32_16x16x32_bf16 v[58:61], v[154:157], v[216:219], v[58:61]
	v_mfma_f32_16x16x32_bf16 v[50:53], v[146:149], v[224:227], v[50:53]
	v_mfma_f32_16x16x32_bf16 v[42:45], v[154:157], v[224:227], v[42:45]
	v_mfma_f32_16x16x32_bf16 v[34:37], v[146:149], v[232:235], v[34:37]
	v_mfma_f32_16x16x32_bf16 v[26:29], v[154:157], v[232:235], v[26:29]
	v_mfma_f32_16x16x32_bf16 v[70:73], v[150:153], v[6:9], v[70:73]
	v_mfma_f32_16x16x32_bf16 v[66:69], v[158:161], v[6:9], v[66:69]
	v_mfma_f32_16x16x32_bf16 v[62:65], v[150:153], v[220:223], v[62:65]
	v_mfma_f32_16x16x32_bf16 v[58:61], v[158:161], v[220:223], v[58:61]
	v_mfma_f32_16x16x32_bf16 v[50:53], v[150:153], v[228:231], v[50:53]
	v_mfma_f32_16x16x32_bf16 v[42:45], v[158:161], v[228:231], v[42:45]
	v_mfma_f32_16x16x32_bf16 v[34:37], v[150:153], v[240:243], v[34:37]
	v_mfma_f32_16x16x32_bf16 v[26:29], v[158:161], v[240:243], v[26:29]
	v_mfma_f32_16x16x32_bf16 v[54:57], v[166:169], v[2:5], v[54:57]
	v_mfma_f32_16x16x32_bf16 v[2:5], v[174:177], v[2:5], v[46:49]
	v_mfma_f32_16x16x32_bf16 v[46:49], v[162:165], v[6:9], v[2:5]
	v_mfma_f32_16x16x32_bf16 v[2:5], v[166:169], v[216:219], v[38:41]
	v_mfma_f32_16x16x32_bf16 v[38:41], v[170:173], v[220:223], v[2:5]
	v_mfma_f32_16x16x32_bf16 v[2:5], v[174:177], v[216:219], v[30:33]
	v_mfma_f32_16x16x32_bf16 v[30:33], v[162:165], v[220:223], v[2:5]
	v_mfma_f32_16x16x32_bf16 v[2:5], v[166:169], v[224:227], v[22:25]
	v_mfma_f32_16x16x32_bf16 v[22:25], v[170:173], v[228:231], v[2:5]
	v_mfma_f32_16x16x32_bf16 v[2:5], v[174:177], v[224:227], v[18:21]
	v_mfma_f32_16x16x32_bf16 v[18:21], v[162:165], v[228:231], v[2:5]
	v_mfma_f32_16x16x32_bf16 v[2:5], v[166:169], v[232:235], v[14:17]
	v_mfma_f32_16x16x32_bf16 v[14:17], v[170:173], v[240:243], v[2:5]
	v_mfma_f32_16x16x32_bf16 v[2:5], v[174:177], v[232:235], v[10:13]
	v_mfma_f32_16x16x32_bf16 v[54:57], v[170:173], v[6:9], v[54:57]
	v_mfma_f32_16x16x32_bf16 v[10:13], v[162:165], v[240:243], v[2:5]
	s_setprio 0
	s_setprio 1
	s_and_b64 vcc, exec, s[40:41]
	s_mov_b64 s[12:13], -1
	s_cbranch_vccnz .LBB0_940
	v_mfma_f32_16x16x32_bf16 v[2:5], v[166:169], v[180:183], v[138:141]
	s_mov_b64 s[12:13], 0
	v_mfma_f32_16x16x32_bf16 v[6:9], v[170:173], v[184:187], v[2:5]
	v_mfma_f32_16x16x32_bf16 v[2:5], v[174:177], v[180:183], v[142:145]
	v_mfma_f32_16x16x32_bf16 v[2:5], v[162:165], v[184:187], v[2:5]
